# expert phase packed-f32 VALU ops replaced by scalar fma/mul/add pairs, pads between them dropped
# speedup vs baseline: 1.0037x; 1.0022x over previous
; __device__ __forceinline__ void phase_expert(const Params& p, int layer, int row0) {
;     ...
;     for (int i0 = 0; i0 < 128; i0 += 4) {
;       u32x4 ua[4]; u32x2 ub[4];
;       float gk[4];
;       int ek[4];
; #pragma unroll
;       for (int k = 0; k < 4; ++k) {
;         ek[k] = __builtin_amdgcn_readfirstlane(ex[i0 + k]);
;         gk[k] = gt[i0 + k];
;         const unsigned char* up = UB + (size_t)ek[k] * 1536;
;         ua[k] = *(const u32x4*)(up + lane * 16); ub[k] = *(const u32x2*)(up + 1024 + lane * 8);
;       }
;       float dk[4];
; #pragma unroll
;       for (int k = 0; k < 4; ++k) {
;         const u32x6 pk = {ua[k][0], ua[k][1], ua[k][2], ua[k][3], ub[k][0], ub[k][1]};
;         const f32x32 f = __builtin_amdgcn_cvt_scalef32_pk32_f32_fp6(pk, 1.0f);
;         float d0 = 0.f, d1 = 0.f;
; #pragma unroll
;         for (int j = 0; j < 32; j += 2) { d0 += f[j] * u[j]; d1 += f[j + 1] * u[j + 1]; }
;         dk[k] = d0 + d1;
;         __builtin_amdgcn_sched_barrier(0);
;       }
; #pragma unroll
;       for (int k = 0; k < 4; ++k) {
;         const unsigned char* vp = VB + (size_t)ek[k] * 1536;
;         ua[k] = *(const u32x4*)(vp + lane * 16); ub[k] = *(const u32x2*)(vp + 1024 + lane * 8);
;       }
.LBB0_1933:
	s_add_u32 s98, s50, 16
	s_addc_u32 s99, s51, 0
	s_cmp_ge_i32 s69, 0x78
	s_cselect_b32 s98, s50, s98
	s_cselect_b32 s99, s51, s99
	global_load_dwordx4 v[252:255], v139, s[98:99]
	global_load_dwordx4 v[134:137], v224, s[50:51]
	s_waitcnt vmcnt(8)
	v_cvt_scalef32_pk32_f32_fp6 v[0:31], v[226:231], 1.0
	v_fma_f32 v0, v0, v150, 0
	v_fma_f32 v1, v1, v151, 0
	v_fma_f32 v0, v2, v152, v0
	v_fma_f32 v1, v3, v153, v1
	v_fma_f32 v0, v4, v154, v0
	v_fma_f32 v1, v5, v155, v1
	v_fma_f32 v0, v6, v156, v0
	v_fma_f32 v1, v7, v157, v1
	v_fma_f32 v0, v8, v144, v0
	v_fma_f32 v1, v9, v145, v1
	v_fma_f32 v0, v10, v146, v0
	v_fma_f32 v1, v11, v147, v1
	v_fma_f32 v0, v12, v148, v0
	v_fma_f32 v1, v13, v149, v1
	v_fma_f32 v0, v14, v158, v0
	v_fma_f32 v1, v15, v159, v1
	v_fma_f32 v0, v16, v160, v0
	v_fma_f32 v1, v17, v161, v1
	v_fma_f32 v0, v18, v164, v0
	v_fma_f32 v1, v19, v165, v1
	v_fma_f32 v0, v20, v170, v0
	v_fma_f32 v1, v21, v171, v1
	v_fma_f32 v0, v22, v174, v0
	v_fma_f32 v1, v23, v175, v1
	v_fma_f32 v0, v24, v162, v0
	v_fma_f32 v1, v25, v163, v1
	v_fma_f32 v0, v26, v166, v0
	v_fma_f32 v1, v27, v167, v1
	v_fma_f32 v0, v28, v172, v0
	v_fma_f32 v1, v29, v173, v1
	v_fma_f32 v56, v30, v176, v0
	v_fma_f32 v57, v31, v177, v1
	s_waitcnt vmcnt(6)
	v_cvt_scalef32_pk32_f32_fp6 v[0:31], v[232:237], 1.0
	v_fma_f32 v0, v0, v150, 0
	v_fma_f32 v1, v1, v151, 0
	v_fma_f32 v0, v2, v152, v0
	v_fma_f32 v1, v3, v153, v1
	v_fma_f32 v0, v4, v154, v0
	v_fma_f32 v1, v5, v155, v1
	v_fma_f32 v0, v6, v156, v0
	v_fma_f32 v1, v7, v157, v1
	v_fma_f32 v0, v8, v144, v0
	v_fma_f32 v1, v9, v145, v1
	v_fma_f32 v0, v10, v146, v0
	v_fma_f32 v1, v11, v147, v1
	v_fma_f32 v0, v12, v148, v0
	v_fma_f32 v1, v13, v149, v1
	v_fma_f32 v0, v14, v158, v0
	v_fma_f32 v1, v15, v159, v1
	v_fma_f32 v0, v16, v160, v0
	v_fma_f32 v1, v17, v161, v1
	v_fma_f32 v0, v18, v164, v0
	v_fma_f32 v1, v19, v165, v1
	v_fma_f32 v0, v20, v170, v0
	v_fma_f32 v1, v21, v171, v1
	v_fma_f32 v0, v22, v174, v0
	v_fma_f32 v1, v23, v175, v1
	v_fma_f32 v0, v24, v162, v0
	v_fma_f32 v1, v25, v163, v1
	v_fma_f32 v0, v26, v166, v0
	v_fma_f32 v1, v27, v167, v1
	v_fma_f32 v0, v28, v172, v0
	v_fma_f32 v1, v29, v173, v1
	v_fma_f32 v58, v30, v176, v0
	v_fma_f32 v59, v31, v177, v1
	s_waitcnt vmcnt(4)
	v_cvt_scalef32_pk32_f32_fp6 v[0:31], v[240:245], 1.0
	v_fma_f32 v0, v0, v150, 0
	v_fma_f32 v1, v1, v151, 0
	v_fma_f32 v0, v2, v152, v0
	v_fma_f32 v1, v3, v153, v1
	v_fma_f32 v0, v4, v154, v0
	v_fma_f32 v1, v5, v155, v1
	v_fma_f32 v0, v6, v156, v0
	v_fma_f32 v1, v7, v157, v1
	v_fma_f32 v0, v8, v144, v0
	v_fma_f32 v1, v9, v145, v1
	v_fma_f32 v0, v10, v146, v0
	v_fma_f32 v1, v11, v147, v1
	v_fma_f32 v0, v12, v148, v0
	v_fma_f32 v1, v13, v149, v1
	v_fma_f32 v0, v14, v158, v0
	v_fma_f32 v1, v15, v159, v1
	v_fma_f32 v0, v16, v160, v0
	v_fma_f32 v1, v17, v161, v1
	v_fma_f32 v0, v18, v164, v0
	v_fma_f32 v1, v19, v165, v1
	v_fma_f32 v0, v20, v170, v0
	v_fma_f32 v1, v21, v171, v1
	v_fma_f32 v0, v22, v174, v0
	v_fma_f32 v1, v23, v175, v1
	v_fma_f32 v0, v24, v162, v0
	v_fma_f32 v1, v25, v163, v1
	v_fma_f32 v0, v26, v166, v0
	v_fma_f32 v1, v27, v167, v1
	v_fma_f32 v0, v28, v172, v0
	v_fma_f32 v1, v29, v173, v1
	v_fma_f32 v96, v30, v176, v0
	v_fma_f32 v97, v31, v177, v1
	s_waitcnt vmcnt(2)
	v_cvt_scalef32_pk32_f32_fp6 v[0:31], v[246:251], 1.0
	v_fma_f32 v0, v0, v150, 0
	v_fma_f32 v1, v1, v151, 0
	v_fma_f32 v0, v2, v152, v0
	v_fma_f32 v1, v3, v153, v1
	v_fma_f32 v0, v4, v154, v0
	v_fma_f32 v1, v5, v155, v1
	v_fma_f32 v0, v6, v156, v0
	v_fma_f32 v1, v7, v157, v1
	v_fma_f32 v0, v8, v144, v0
	v_fma_f32 v1, v9, v145, v1
	v_fma_f32 v0, v10, v146, v0
	v_fma_f32 v1, v11, v147, v1
	v_fma_f32 v0, v12, v148, v0
	v_fma_f32 v1, v13, v149, v1
	v_fma_f32 v0, v14, v158, v0
	v_fma_f32 v1, v15, v159, v1
	v_fma_f32 v0, v16, v160, v0
	v_fma_f32 v1, v17, v161, v1
	v_fma_f32 v0, v18, v164, v0
	v_fma_f32 v1, v19, v165, v1
	v_fma_f32 v0, v20, v170, v0
	v_fma_f32 v1, v21, v171, v1
	v_fma_f32 v0, v22, v174, v0
	v_fma_f32 v1, v23, v175, v1
	v_fma_f32 v0, v24, v162, v0
	v_fma_f32 v1, v25, v163, v1
	v_fma_f32 v0, v26, v166, v0
	v_fma_f32 v1, v27, v167, v1
	v_fma_f32 v0, v28, v172, v0
	v_fma_f32 v1, v29, v173, v1
	v_fma_f32 v208, v30, v176, v0
	v_fma_f32 v209, v31, v177, v1
	s_add_u32 s78, s11, s73
	s_addc_u32 s79, s13, 0
	v_lshl_add_u64 v[0:1], s[78:79], 0, v[138:139]
	v_lshl_add_u64 v[2:3], s[78:79], 0, v[142:143]
	global_load_dwordx4 v[32:35], v[0:1], off
	global_load_dwordx2 v[36:37], v[2:3], off offset:1024
	s_add_u32 s78, s11, s49
	s_addc_u32 s79, s13, 0
	v_lshl_add_u64 v[0:1], s[78:79], 0, v[138:139]
	v_lshl_add_u64 v[2:3], s[78:79], 0, v[142:143]
	global_load_dwordx4 v[38:41], v[0:1], off
	global_load_dwordx2 v[42:43], v[2:3], off offset:1024
	s_add_u32 s78, s11, s71
	s_addc_u32 s79, s13, 0
	v_lshl_add_u64 v[0:1], s[78:79], 0, v[138:139]
	v_lshl_add_u64 v[2:3], s[78:79], 0, v[142:143]
	global_load_dwordx4 v[98:101], v[0:1], off
	global_load_dwordx2 v[102:103], v[2:3], off offset:1024
	s_add_u32 s78, s11, s77
	s_addc_u32 s79, s13, 0
	v_lshl_add_u64 v[0:1], s[78:79], 0, v[138:139]
	v_lshl_add_u64 v[2:3], s[78:79], 0, v[142:143]
	global_load_dwordx4 v[128:131], v[0:1], off
	global_load_dwordx2 v[132:133], v[2:3], off offset:1024
	s_waitcnt vmcnt(9)
; __device__ __forceinline__ void phase_expert(const Params& p, int layer, int row0) {
;     ...
; #pragma unroll
;       for (int k = 0; k < 4; ++k) {
;         ek[k] = __builtin_amdgcn_readfirstlane(ex[i0 + k]);
;         gk[k] = gt[i0 + k];
;         const unsigned char* up = UB + (size_t)ek[k] * 1536;
;         ua[k] = *(const u32x4*)(up + lane * 16); ub[k] = *(const u32x2*)(up + 1024 + lane * 8);
;     ...
; #pragma unroll
;       for (int o = 32; o >= 1; o >>= 1) {
; #pragma unroll
;         for (int k = 0; k < 4; ++k) dk[k] += __shfl_xor(dk[k], o);
;       }
; #pragma unroll
;       for (int k = 0; k < 4; ++k) {
;         const float a = dk[k] * (1.f / SC_U);
;         const float w = gk[k] * (0.5f * a * (1.f + my_erf(a * 0.7071067811865476f)));
;         const u32x6 pk = {ua[k][0], ua[k][1], ua[k][2], ua[k][3], ub[k][0], ub[k][1]};
;         const f32x32 f = __builtin_amdgcn_cvt_scalef32_pk32_f32_fp6(pk, 1.0f);
; #pragma unroll
;         for (int j = 0; j < 32; ++j) y[j] += w * f[j];
;         __builtin_amdgcn_sched_barrier(0);
;       }
	v_readfirstlane_b32 s73, v252
	v_readfirstlane_b32 s49, v253
	v_readfirstlane_b32 s71, v254
	v_readfirstlane_b32 s77, v255
	s_mulk_i32 s73, 0x600
	s_mulk_i32 s49, 0x600
	s_mulk_i32 s71, 0x600
	s_mulk_i32 s77, 0x600
	s_add_u32 s78, s2, s73
	s_addc_u32 s79, s3, 0
	v_lshl_add_u64 v[0:1], s[78:79], 0, v[138:139]
	v_lshl_add_u64 v[2:3], s[78:79], 0, v[142:143]
	global_load_dwordx4 v[226:229], v[0:1], off
	global_load_dwordx2 v[230:231], v[2:3], off offset:1024
	s_add_u32 s78, s2, s49
	s_addc_u32 s79, s3, 0
	v_lshl_add_u64 v[0:1], s[78:79], 0, v[138:139]
	v_lshl_add_u64 v[2:3], s[78:79], 0, v[142:143]
	global_load_dwordx4 v[232:235], v[0:1], off
	global_load_dwordx2 v[236:237], v[2:3], off offset:1024
	s_add_u32 s78, s2, s71
	s_addc_u32 s79, s3, 0
	v_lshl_add_u64 v[0:1], s[78:79], 0, v[138:139]
	v_lshl_add_u64 v[2:3], s[78:79], 0, v[142:143]
	global_load_dwordx4 v[240:243], v[0:1], off
	global_load_dwordx2 v[244:245], v[2:3], off offset:1024
	s_add_u32 s78, s2, s77
	s_addc_u32 s79, s3, 0
	v_lshl_add_u64 v[0:1], s[78:79], 0, v[138:139]
	v_lshl_add_u64 v[2:3], s[78:79], 0, v[142:143]
	global_load_dwordx4 v[246:249], v[0:1], off
	global_load_dwordx2 v[250:251], v[2:3], off offset:1024
	s_waitcnt vmcnt(14)
	v_cvt_scalef32_pk32_f32_fp6 v[0:31], v[32:37], 1.0
	v_mov_b32_e32 v32, v59
	v_mov_b32_e32 v33, v57
	v_mov_b32_e32 v59, v56
	v_add_f32_e64 v32, v32, v58
	v_add_f32_e64 v33, v33, v59
	ds_bpermute_b32 v35, v217, v33
	ds_bpermute_b32 v34, v217, v32
	s_waitcnt vmcnt(12)
	v_cvt_scalef32_pk32_f32_fp6 v[64:95], v[38:43], 1.0
	s_waitcnt lgkmcnt(0)
	v_add_f32_e64 v32, v32, v34
	v_add_f32_e64 v33, v33, v35
	ds_bpermute_b32 v35, v218, v33
	ds_bpermute_b32 v34, v218, v32
	s_waitcnt lgkmcnt(0)
	v_add_f32_e64 v32, v32, v34
	v_add_f32_e64 v33, v33, v35
	ds_bpermute_b32 v35, v219, v33
	ds_bpermute_b32 v34, v219, v32
	s_waitcnt lgkmcnt(0)
	v_add_f32_e64 v32, v32, v34
	v_add_f32_e64 v33, v33, v35
	ds_bpermute_b32 v35, v220, v33
	ds_bpermute_b32 v34, v220, v32
	s_waitcnt lgkmcnt(0)
	v_add_f32_e64 v32, v32, v34
	v_add_f32_e64 v33, v33, v35
	ds_bpermute_b32 v35, v221, v33
	ds_bpermute_b32 v34, v221, v32
	s_waitcnt lgkmcnt(0)
	v_add_f32_e64 v32, v32, v34
	v_add_f32_e64 v33, v33, v35
	ds_bpermute_b32 v35, v222, v33
	ds_bpermute_b32 v34, v222, v32
	s_waitcnt lgkmcnt(0)
	v_add_f32_e64 v32, v32, v34
	v_add_f32_e64 v33, v33, v35
	v_mul_f32_e64 v32, v32, s10
	v_mul_f32_e64 v33, v33, s10
	v_mul_f32_e64 v34, v32, s12
	v_mul_f32_e64 v35, v33, s12
	v_mul_f32_e32 v36, 0.5, v33
	v_fma_f32 v33, |v35|, s53, 1.0
	v_div_scale_f32 v45, s[0:1], v33, v33, 1.0
	v_rcp_f32_e32 v48, v45
	v_div_scale_f32 v46, vcc, 1.0, v33, 1.0
	v_mul_f32_e64 v37, |v35|, -|v35|
	v_fma_f32 v51, -v45, v48, 1.0
	v_fmac_f32_e32 v48, v51, v48
	v_mul_f32_e32 v51, v46, v48
	v_fma_f32 v53, -v45, v51, v46
	v_fmac_f32_e32 v51, v53, v48
	v_fma_f32 v45, -v45, v51, v46
	v_div_fmas_f32 v45, v45, v48, v51
	v_div_fixup_f32 v33, v45, v33, 1.0
	v_fma_f32 v44, |v34|, s53, 1.0
	v_mul_f32_e32 v37, 0x3fb8aa3b, v37
	v_fmamk_f32 v45, v33, 0x3f87dc22, v225
	v_div_scale_f32 v47, s[0:1], v44, v44, 1.0
	v_exp_f32_e32 v37, v37
	v_fmaak_f32 v45, v33, v45, 0x3fb5f0e3
	v_rcp_f32_e32 v49, v47
	v_fmaak_f32 v45, v33, v45, 0xbe91a98e
	v_fmaak_f32 v45, v33, v45, 0x3e827906
	v_mul_f32_e32 v33, v33, v45
	v_fma_f32 v33, -v37, v33, 1.0
	v_cmp_gt_f32_e32 vcc, 0, v35
	v_fma_f32 v52, -v47, v49, 1.0
	v_div_scale_f32 v50, s[0:1], 1.0, v44, 1.0
	v_cndmask_b32_e64 v33, v33, -v33, vcc
	v_fmac_f32_e32 v49, v52, v49
	v_add_f32_e32 v33, 1.0, v33
	v_mul_f32_e32 v52, v50, v49
	v_mul_f32_e32 v33, v36, v33
	v_mul_f32_e32 v134, v134, v33
	v_fma_f32 v33, -v47, v52, v50
	v_fmac_f32_e32 v52, v33, v49
	v_fma_f32 v33, -v47, v52, v50
	s_mov_b64 vcc, s[0:1]
	v_div_fmas_f32 v33, v33, v49, v52
	v_div_fixup_f32 v33, v33, v44, 1.0
	v_mul_f32_e64 v36, |v34|, -|v34|
	v_fmamk_f32 v35, v33, 0x3f87dc22, v225
	v_mul_f32_e32 v36, 0x3fb8aa3b, v36
	v_fmaak_f32 v35, v33, v35, 0x3fb5f0e3
	v_exp_f32_e32 v36, v36
	v_fmaak_f32 v35, v33, v35, 0xbe91a98e
	v_fmaak_f32 v35, v33, v35, 0x3e827906
	v_mul_f32_e32 v33, v33, v35
	v_fma_f32 v33, -v36, v33, 1.0
	v_cmp_gt_f32_e32 vcc, 0, v34
	v_mul_f32_e32 v32, 0.5, v32
	s_nop 0
	v_cndmask_b32_e64 v33, v33, -v33, vcc
	v_add_f32_e32 v33, 1.0, v33
	v_mul_f32_e32 v32, v32, v33
	v_mul_f32_e32 v210, v135, v32
	s_waitcnt vmcnt(10)
	v_cvt_scalef32_pk32_f32_fp6 v[32:63], v[98:103], 1.0
	v_mov_b32_e32 v212, v209
	v_mov_b32_e32 v213, v97
	v_mov_b32_e32 v209, v96
	s_waitcnt vmcnt(8)
	v_cvt_scalef32_pk32_f32_fp6 v[96:127], v[128:133], 1.0
	v_fma_f32 v0, v0, v134, v206
	v_fma_f32 v1, v1, v134, v207
	v_add_f32_e64 v128, v212, v208
	v_add_f32_e64 v129, v213, v209
	v_fma_f32 v0, v64, v210, v0
	v_fma_f32 v1, v65, v210, v1
	ds_bpermute_b32 v65, v217, v129
	ds_bpermute_b32 v64, v217, v128
	v_fma_f32 v2, v2, v134, v204
	v_fma_f32 v3, v3, v134, v205
	v_fma_f32 v4, v4, v134, v202
	v_fma_f32 v5, v5, v134, v203
	v_fma_f32 v2, v66, v210, v2
	v_fma_f32 v3, v67, v210, v3
	v_fma_f32 v6, v6, v134, v200
	v_fma_f32 v7, v7, v134, v201
	s_waitcnt lgkmcnt(0)
	v_add_f32_e64 v64, v128, v64
	v_add_f32_e64 v65, v129, v65
	ds_bpermute_b32 v67, v218, v65
	ds_bpermute_b32 v66, v218, v64
	v_fma_f32 v8, v8, v134, v198
	v_fma_f32 v9, v9, v134, v199
	v_fma_f32 v4, v68, v210, v4
	v_fma_f32 v5, v69, v210, v5
	v_fma_f32 v10, v10, v134, v196
	v_fma_f32 v11, v11, v134, v197
	v_fma_f32 v12, v12, v134, v194
	v_fma_f32 v13, v13, v134, v195
	s_waitcnt lgkmcnt(0)
	v_add_f32_e64 v64, v64, v66
	v_add_f32_e64 v65, v65, v67
	ds_bpermute_b32 v67, v219, v65
	ds_bpermute_b32 v66, v219, v64
	v_fma_f32 v6, v70, v210, v6
	v_fma_f32 v7, v71, v210, v7
	v_fma_f32 v8, v72, v210, v8
	v_fma_f32 v9, v73, v210, v9
	v_fma_f32 v10, v74, v210, v10
	v_fma_f32 v11, v75, v210, v11
	v_fma_f32 v12, v76, v210, v12
	v_fma_f32 v13, v77, v210, v13
	s_waitcnt lgkmcnt(0)
; __device__ __forceinline__ void phase_expert(const Params& p, int layer, int row0) {
;     ...
; #pragma unroll
;       for (int o = 32; o >= 1; o >>= 1) {
; #pragma unroll
;         for (int k = 0; k < 4; ++k) dk[k] += __shfl_xor(dk[k], o);
;       }
; #pragma unroll
;       for (int k = 0; k < 4; ++k) {
;         const float a = dk[k] * (1.f / SC_U);
;         const float w = gk[k] * (0.5f * a * (1.f + my_erf(a * 0.7071067811865476f)));
;         const u32x6 pk = {ua[k][0], ua[k][1], ua[k][2], ua[k][3], ub[k][0], ub[k][1]};
;         const f32x32 f = __builtin_amdgcn_cvt_scalef32_pk32_f32_fp6(pk, 1.0f);
; #pragma unroll
;         for (int j = 0; j < 32; ++j) y[j] += w * f[j];
;         __builtin_amdgcn_sched_barrier(0);
;       }
	v_add_f32_e64 v64, v64, v66
	v_add_f32_e64 v65, v65, v67
	ds_bpermute_b32 v67, v220, v65
	ds_bpermute_b32 v66, v220, v64
	v_fma_f32 v14, v14, v134, v192
	v_fma_f32 v15, v15, v134, v193
	v_fma_f32 v16, v16, v134, v190
	v_fma_f32 v17, v17, v134, v191
	v_fma_f32 v14, v78, v210, v14
	v_fma_f32 v15, v79, v210, v15
	v_fma_f32 v16, v80, v210, v16
	v_fma_f32 v17, v81, v210, v17
	s_waitcnt lgkmcnt(0)
	v_add_f32_e64 v64, v64, v66
	v_add_f32_e64 v65, v65, v67
	ds_bpermute_b32 v67, v221, v65
	ds_bpermute_b32 v66, v221, v64
	v_fma_f32 v18, v18, v134, v188
	v_fma_f32 v19, v19, v134, v189
	v_fma_f32 v20, v20, v134, v186
	v_fma_f32 v21, v21, v134, v187
	v_fma_f32 v22, v22, v134, v184
	v_fma_f32 v23, v23, v134, v185
	v_fma_f32 v24, v24, v134, v182
	v_fma_f32 v25, v25, v134, v183
	s_waitcnt lgkmcnt(0)
	v_add_f32_e64 v64, v64, v66
	v_add_f32_e64 v65, v65, v67
	ds_bpermute_b32 v67, v222, v65
	ds_bpermute_b32 v66, v222, v64
	v_fma_f32 v26, v26, v134, v180
	v_fma_f32 v27, v27, v134, v181
	v_fma_f32 v28, v28, v134, v178
	v_fma_f32 v29, v29, v134, v179
	v_fma_f32 v30, v30, v134, v168
	v_fma_f32 v31, v31, v134, v169
	v_fma_f32 v18, v82, v210, v18
	v_fma_f32 v19, v83, v210, v19
	s_waitcnt lgkmcnt(0)
	v_add_f32_e64 v64, v64, v66
	v_add_f32_e64 v65, v65, v67
	v_fma_f32 v20, v84, v210, v20
	v_fma_f32 v21, v85, v210, v21
	v_mul_f32_e64 v64, v64, s10
	v_mul_f32_e64 v65, v65, s10
	v_fma_f32 v22, v86, v210, v22
	v_fma_f32 v23, v87, v210, v23
	v_mul_f32_e64 v66, v64, s12
	v_mul_f32_e64 v67, v65, s12
	v_mul_f32_e32 v68, 0.5, v65
	v_mul_f32_e32 v65, 0.5, v64
	v_fma_f32 v64, |v67|, s53, 1.0
	v_fma_f32 v70, |v66|, s53, 1.0
	v_div_scale_f32 v72, s[0:1], v64, v64, 1.0
	v_div_scale_f32 v74, s[0:1], v70, v70, 1.0
	v_rcp_f32_e32 v76, v72
	v_rcp_f32_e32 v77, v74
	v_div_scale_f32 v73, vcc, 1.0, v64, 1.0
	v_fma_f32 v78, -v72, v76, 1.0
	v_fma_f32 v79, -v74, v77, 1.0
	v_fmac_f32_e32 v76, v78, v76
	v_div_scale_f32 v75, s[0:1], 1.0, v70, 1.0
	v_fmac_f32_e32 v77, v79, v77
	v_mul_f32_e32 v78, v73, v76
	v_mul_f32_e32 v79, v75, v77
	v_fma_f32 v80, -v72, v78, v73
	v_fma_f32 v81, -v74, v79, v75
	v_fmac_f32_e32 v78, v80, v76
	v_fmac_f32_e32 v79, v81, v77
	v_fma_f32 v72, -v72, v78, v73
	v_fma_f32 v73, -v74, v79, v75
	v_div_fmas_f32 v72, v72, v76, v78
	s_mov_b64 vcc, s[0:1]
	v_mul_f32_e64 v69, |v67|, -|v67|
	v_div_fixup_f32 v64, v72, v64, 1.0
	v_div_fmas_f32 v72, v73, v77, v79
	v_mul_f32_e64 v71, |v66|, -|v66|
	v_mul_f32_e32 v69, 0x3fb8aa3b, v69
	v_fmamk_f32 v73, v64, 0x3f87dc22, v225
	v_div_fixup_f32 v70, v72, v70, 1.0
	v_mul_f32_e32 v71, 0x3fb8aa3b, v71
	v_exp_f32_e32 v69, v69
	v_fmaak_f32 v72, v64, v73, 0x3fb5f0e3
	v_fmamk_f32 v73, v70, 0x3f87dc22, v225
	v_exp_f32_e32 v71, v71
	v_fmaak_f32 v72, v64, v72, 0xbe91a98e
	v_fmaak_f32 v73, v70, v73, 0x3fb5f0e3
	v_fmaak_f32 v72, v64, v72, 0x3e827906
	v_fmaak_f32 v73, v70, v73, 0xbe91a98e
	v_mul_f32_e32 v64, v64, v72
	v_fmaak_f32 v72, v70, v73, 0x3e827906
	v_fma_f32 v64, -v69, v64, 1.0
	v_cmp_gt_f32_e32 vcc, 0, v67
	v_mul_f32_e32 v67, v70, v72
	v_fma_f32 v67, -v71, v67, 1.0
	v_cmp_gt_f32_e64 s[0:1], 0, v66
	v_cndmask_b32_e64 v64, v64, -v64, vcc
	v_add_f32_e32 v64, 1.0, v64
	v_cndmask_b32_e64 v66, v67, -v67, s[0:1]
	v_mul_f32_e32 v64, v68, v64
	v_add_f32_e32 v66, 1.0, v66
	v_fma_f32 v24, v88, v210, v24
	v_fma_f32 v25, v89, v210, v25
	v_fma_f32 v26, v90, v210, v26
	v_fma_f32 v27, v91, v210, v27
	v_fma_f32 v28, v92, v210, v28
	v_fma_f32 v29, v93, v210, v29
	v_fma_f32 v30, v94, v210, v30
	v_fma_f32 v31, v95, v210, v31
	v_mul_f32_e32 v64, v136, v64
	v_mul_f32_e32 v65, v65, v66
	v_mul_f32_e32 v66, v137, v65
	v_fma_f32 v0, v32, v64, v0
	v_fma_f32 v1, v33, v64, v1
	v_fma_f32 v2, v34, v64, v2
	v_fma_f32 v3, v35, v64, v3
	v_fma_f32 v4, v36, v64, v4
	v_fma_f32 v5, v37, v64, v5
	v_fma_f32 v6, v38, v64, v6
	v_fma_f32 v7, v39, v64, v7
	v_fma_f32 v8, v40, v64, v8
	v_fma_f32 v9, v41, v64, v9
	v_fma_f32 v10, v42, v64, v10
	v_fma_f32 v11, v43, v64, v11
	v_fma_f32 v12, v44, v64, v12
	v_fma_f32 v13, v45, v64, v13
	v_fma_f32 v14, v46, v64, v14
	v_fma_f32 v15, v47, v64, v15
	v_fma_f32 v16, v48, v64, v16
	v_fma_f32 v17, v49, v64, v17
	v_fma_f32 v18, v50, v64, v18
	v_fma_f32 v19, v51, v64, v19
	v_fma_f32 v20, v52, v64, v20
	v_fma_f32 v21, v53, v64, v21
	v_fma_f32 v22, v54, v64, v22
	v_fma_f32 v23, v55, v64, v23
	v_fma_f32 v24, v56, v64, v24
	v_fma_f32 v25, v57, v64, v25
	v_fma_f32 v26, v58, v64, v26
	v_fma_f32 v27, v59, v64, v27
	v_fma_f32 v28, v60, v64, v28
	v_fma_f32 v29, v61, v64, v29
	v_fma_f32 v30, v62, v64, v30
	v_fma_f32 v31, v63, v64, v31
	v_fma_f32 v206, v96, v66, v0
	v_fma_f32 v207, v97, v66, v1
	v_fma_f32 v204, v98, v66, v2
	v_fma_f32 v205, v99, v66, v3
	v_fma_f32 v202, v100, v66, v4
	v_fma_f32 v203, v101, v66, v5
	v_fma_f32 v200, v102, v66, v6
	v_fma_f32 v201, v103, v66, v7
	v_fma_f32 v198, v104, v66, v8
	v_fma_f32 v199, v105, v66, v9
	v_fma_f32 v196, v106, v66, v10
	v_fma_f32 v197, v107, v66, v11
	v_fma_f32 v194, v108, v66, v12
	v_fma_f32 v195, v109, v66, v13
	v_fma_f32 v192, v110, v66, v14
	v_fma_f32 v193, v111, v66, v15
	v_fma_f32 v190, v112, v66, v16
	v_fma_f32 v191, v113, v66, v17
	v_fma_f32 v188, v114, v66, v18
	v_fma_f32 v189, v115, v66, v19
	v_fma_f32 v186, v116, v66, v20
	v_fma_f32 v187, v117, v66, v21
	v_fma_f32 v184, v118, v66, v22
	v_fma_f32 v185, v119, v66, v23
	v_fma_f32 v182, v120, v66, v24
	v_fma_f32 v183, v121, v66, v25
	v_fma_f32 v180, v122, v66, v26
	v_fma_f32 v181, v123, v66, v27
	v_fma_f32 v178, v124, v66, v28
	v_fma_f32 v179, v125, v66, v29
	v_fma_f32 v168, v126, v66, v30
	v_fma_f32 v169, v127, v66, v31
	s_add_i32 s69, s69, 4
	s_add_u32 s50, s50, 16
	s_addc_u32 s51, s51, 0
	s_cmpk_gt_u32 s69, 0x7b
	s_cbranch_scc0 .LBB0_1933
; DI const float* modp(const Params& p, int layer, int v) { return (const float*)(p.ws + OFF_MOD) + (size_t)(layer * 2 + v) * 12288; }
; __device__ __forceinline__ void phase_expert(const Params& p, int layer, int row0) {
;     ...
;     int lane2 = lane; asm volatile("" : "+v"(lane2));
;     const int v = row < NCTX ? 1 : 0;
;     const float* md = modp(p, layer, v);
;     float pre[32];
;     float s = 0.f;
; #pragma unroll
;     for (int c = 0; c < 2; ++c) {
; #pragma unroll
;       for (int q4 = 0; q4 < 4; ++q4) {
;         const int col = c * 1024 + lane2 * 16 + q4 * 4;
;         const f32x4 a = *(const f32x4*)(XR + (size_t)row * LDF + col);
;         const f32x4 g2 = *(const f32x4*)(md + 10240 + col);
; #pragma unroll
;         for (int e = 0; e < 4; ++e) {
;           const float pv = ALPHA * a[e] + g2[e] * (y[c * 16 + q4 * 4 + e] * (1.f / SC_V));
;           pre[c * 16 + q4 * 4 + e] = pv; s += pv;
;         }
;       }
;     }
;     const float mu = wave_sum(s) * (1.f / 2048.f);
	v_mov_b32_e32 v0, v216
	s_cmpk_lt_i32 s48, 0x100
	s_cselect_b32 s1, 0xc000, 0
	v_lshlrev_b32_e32 v0, 4, v0
	s_cselect_b32 s0, s60, 0x18000
	s_add_u32 s50, s46, s1
	v_ashrrev_i32_e32 v1, 31, v0
	s_addc_u32 s51, s47, 0
	v_lshlrev_b64 v[8:9], 2, v[0:1]
	v_lshl_add_u64 v[2:3], s[50:51], 0, v[8:9]
	s_mul_hi_i32 s1, s48, 0x2080
	s_mulk_i32 s48, 0x2080
	v_lshl_add_u64 v[4:5], v[2:3], 0, s[14:15]
	v_lshl_add_u64 v[58:59], v[2:3], 0, s[20:21]
	v_add_co_u32_e32 v2, vcc, s62, v2
	s_add_u32 s48, s34, s48
	s_nop 0
	v_addc_co_u32_e32 v3, vcc, 0, v3, vcc
	s_addc_u32 s49, s35, s1
	global_load_dwordx4 v[10:13], v[4:5], off offset:32
	global_load_dwordx4 v[14:17], v[4:5], off offset:16
	global_load_dwordx4 v[18:21], v[58:59], off offset:32
	global_load_dwordx4 v[22:25], v[58:59], off offset:48
	global_load_dwordx4 v[26:29], v[2:3], off offset:-4096
	global_load_dwordx4 v[34:37], v[2:3], off
	global_load_dwordx4 v[30:33], v[4:5], off offset:48
	v_lshl_add_u64 v[4:5], s[48:49], 0, v[8:9]
	v_lshl_add_u64 v[6:7], v[4:5], 0, s[18:19]
	v_add_co_u32_e32 v2, vcc, s61, v4
	global_load_dwordx4 v[38:41], v[6:7], off offset:48
	global_load_dwordx4 v[42:45], v[4:5], off offset:16
	global_load_dwordx4 v[46:49], v[4:5], off
	global_load_dwordx4 v[50:53], v[4:5], off offset:32
	global_load_dwordx4 v[54:57], v[4:5], off offset:48
	s_nop 0
	global_load_dwordx4 v[58:61], v[58:59], off offset:16
	v_addc_co_u32_e32 v3, vcc, 0, v5, vcc
	global_load_dwordx4 v[62:65], v[2:3], off
	global_load_dwordx4 v[66:69], v[6:7], off offset:32
	global_load_dwordx4 v[70:73], v[6:7], off offset:16
	v_mul_f32_e64 v74, v206, s16
	v_mul_f32_e64 v75, v207, s16
	v_mul_f32_e64 v102, v178, s16
	v_mul_f32_e64 v103, v179, s16
	v_mul_f32_e64 v76, v204, s16
	v_mul_f32_e64 v77, v205, s16
	v_mul_f32_e64 v78, v202, s16
	v_mul_f32_e64 v79, v203, s16
	v_mul_f32_e64 v104, v168, s16
	v_mul_f32_e64 v105, v169, s16
	v_mul_f32_e64 v84, v196, s16
	v_mul_f32_e64 v85, v197, s16
	v_mul_f32_e64 v94, v186, s16
	v_mul_f32_e64 v95, v187, s16
	v_mul_f32_e64 v80, v200, s16
	v_mul_f32_e64 v81, v201, s16
	v_mul_f32_e64 v82, v198, s16
	v_mul_f32_e64 v83, v199, s16
	v_mul_f32_e64 v86, v194, s16
	v_mul_f32_e64 v87, v195, s16
	v_mul_f32_e64 v88, v192, s16
	v_mul_f32_e64 v89, v193, s16
	v_mul_f32_e64 v90, v190, s16
	v_mul_f32_e64 v91, v191, s16
	v_mul_f32_e64 v92, v188, s16
	v_mul_f32_e64 v93, v189, s16
	v_mul_f32_e64 v96, v184, s16
	v_mul_f32_e64 v97, v185, s16
	v_mul_f32_e64 v98, v182, s16
	v_mul_f32_e64 v99, v183, s16
	v_mul_f32_e64 v100, v180, s16
	v_mul_f32_e64 v101, v181, s16
	s_add_u32 s0, s46, s0
	s_addc_u32 s1, s47, 0
	s_add_u32 s48, s8, s68
	s_addc_u32 s49, s9, s67
	v_add_u32_e32 v215, s52, v215
	s_waitcnt vmcnt(15)
	v_mul_f32_e64 v12, v84, v12
	v_mul_f32_e64 v13, v85, v13
	s_waitcnt vmcnt(14)
	v_mul_f32_e64 v14, v78, v14
	v_mul_f32_e64 v15, v79, v15
	s_waitcnt vmcnt(12)
	v_mul_f32_e64 v22, v102, v22
	v_mul_f32_e64 v23, v103, v23
	s_waitcnt vmcnt(11)
	v_mul_f32_e64 v26, v74, v26
	v_mul_f32_e64 v27, v75, v27
	v_mul_f32_e64 v24, v104, v24
	v_mul_f32_e64 v25, v105, v25
	v_mul_f32_e64 v28, v76, v28
	v_mul_f32_e64 v29, v77, v29
	s_waitcnt vmcnt(8)
	v_fma_f32 v74, v38, s24, v22
	v_fma_f32 v75, v39, s24, v23
	s_waitcnt vmcnt(6)
	v_fma_f32 v22, v46, s24, v26
	v_fma_f32 v23, v47, s24, v27
	v_fma_f32 v40, v40, s24, v24
	v_fma_f32 v41, v41, s24, v25
	v_fma_f32 v14, v42, s24, v14
	v_fma_f32 v15, v43, s24, v15
	v_fma_f32 v42, v48, s24, v28
	v_fma_f32 v43, v49, s24, v29
	s_waitcnt vmcnt(3)
	v_mul_f32_e64 v24, v94, v58
	v_mul_f32_e64 v25, v95, v59
	v_add_f32_e32 v28, 0, v22
	v_fma_f32 v12, v52, s24, v12
	v_fma_f32 v13, v53, s24, v13
	s_waitcnt vmcnt(0)
	v_fma_f32 v52, v70, s24, v24
	v_fma_f32 v53, v71, s24, v25
	v_add_f32_e32 v24, v23, v28
	v_add_f32_e32 v24, v42, v24
	v_add_f32_e32 v24, v43, v24
	v_mul_f32_e64 v16, v80, v16
	v_mul_f32_e64 v17, v81, v17
	v_add_f32_e32 v24, v14, v24
	v_fma_f32 v16, v44, s24, v16
	v_fma_f32 v17, v45, s24, v17
	v_add_f32_e32 v24, v15, v24
	v_mul_f32_e64 v10, v82, v10
	v_mul_f32_e64 v11, v83, v11
	v_add_f32_e32 v24, v16, v24
	v_fma_f32 v10, v50, s24, v10
	v_fma_f32 v11, v51, s24, v11
	v_add_f32_e32 v24, v17, v24
	v_add_f32_e32 v24, v10, v24
	v_add_f32_e32 v24, v11, v24
	v_mul_f32_e64 v30, v86, v30
	v_mul_f32_e64 v31, v87, v31
	v_add_f32_e32 v24, v12, v24
	v_fma_f32 v44, v54, s24, v30
	v_fma_f32 v45, v55, s24, v31
	v_add_f32_e32 v24, v13, v24
	v_mul_f32_e64 v32, v88, v32
	v_mul_f32_e64 v33, v89, v33
	v_add_f32_e32 v24, v44, v24
	v_fma_f32 v46, v56, s24, v32
	v_fma_f32 v47, v57, s24, v33
	v_add_f32_e32 v24, v45, v24
	v_mul_f32_e64 v34, v90, v34
	v_mul_f32_e64 v35, v91, v35
	v_add_f32_e32 v24, v46, v24
	v_fma_f32 v48, v62, s24, v34
	v_fma_f32 v49, v63, s24, v35
	v_add_f32_e32 v24, v47, v24
	v_mul_f32_e64 v36, v92, v36
	v_mul_f32_e64 v37, v93, v37
	v_add_f32_e32 v24, v48, v24
	v_fma_f32 v50, v64, s24, v36
	v_fma_f32 v51, v65, s24, v37
	v_add_f32_e32 v24, v49, v24
	v_add_f32_e32 v24, v50, v24
	v_add_f32_e32 v24, v51, v24
	v_mul_f32_e64 v26, v96, v60
	v_mul_f32_e64 v27, v97, v61
	v_add_f32_e32 v24, v52, v24
	v_fma_f32 v54, v72, s24, v26
	v_fma_f32 v55, v73, s24, v27
	v_add_f32_e32 v24, v53, v24
	v_mul_f32_e64 v18, v98, v18
	v_mul_f32_e64 v19, v99, v19
	v_add_f32_e32 v24, v54, v24
	v_fma_f32 v18, v66, s24, v18
	v_fma_f32 v19, v67, s24, v19
	v_add_f32_e32 v24, v55, v24
	v_add_f32_e32 v24, v18, v24
	v_mul_f32_e64 v20, v100, v20
	v_mul_f32_e64 v21, v101, v21
	v_add_f32_e32 v24, v19, v24
	v_fma_f32 v20, v68, s24, v20
	v_fma_f32 v21, v69, s24, v21
	v_lshl_add_u64 v[56:57], s[42:43], 0, v[8:9]
	v_add_f32_e32 v24, v20, v24
	v_add_f32_e32 v24, v21, v24
	v_add_f32_e32 v24, v74, v24
	v_add_f32_e32 v24, v75, v24
	v_add_f32_e32 v24, v40, v24
	v_add_f32_e32 v24, v41, v24
	ds_bpermute_b32 v25, v217, v24
	v_lshl_add_u64 v[58:59], s[44:45], 0, v[8:9]
	v_lshl_add_u64 v[8:9], s[0:1], 0, v[8:9]
	s_waitcnt lgkmcnt(0)
; DI unsigned pk2(float a, float b) { f32x2 v = {a, b}; bf2_t r = __builtin_convertvector(v, bf2_t); return __builtin_bit_cast(unsigned, r); }
; DI const float* modp(const Params& p, int layer, int v) { return (const float*)(p.ws + OFF_MOD) + (size_t)(layer * 2 + v) * 12288; }
; __device__ __forceinline__ void phase_expert(const Params& p, int layer, int row0) {
;     ...
;     const float mu = wave_sum(s) * (1.f / 2048.f);
;     float q = 0.f;
; #pragma unroll
;     for (int e = 0; e < 32; ++e) { float d = pre[e] - mu; q += d * d; }
;     const float rstd = rsqrtf(wave_sum(q) * (1.f / 2048.f) + LN_EPS);
;     const float* mdn = modp(p, 1, v);
; #pragma unroll
;     for (int c = 0; c < 2; ++c) {
; #pragma unroll
;       for (int q8 = 0; q8 < 2; ++q8) {
;         const int col = c * 1024 + lane2 * 16 + q8 * 8;
;         float o[8];
; #pragma unroll
;         for (int e = 0; e < 8; ++e) o[e] = (pre[c * 16 + q8 * 8 + e] - mu) * rstd * G[col + e] + B[col + e];
;         if (layer == 0) {
;           *(f32x4*)(XR + (size_t)row * LDF + col) = f32x4{o[0], o[1], o[2], o[3]};
;           *(f32x4*)(XR + (size_t)row * LDF + col + 4) = f32x4{o[4], o[5], o[6], o[7]};
;           float z[8];
; #pragma unroll
;           for (int e = 0; e < 8; ++e) z[e] = o[e] * (1.f + mdn[2048 + col + e]) + mdn[col + e];
;           *(u32x4*)(XMo + (size_t)row * LDX + col) = u32x4{pk2(z[0], z[1]), pk2(z[2], z[3]), pk2(z[4], z[5]), pk2(z[6], z[7])};
	v_add_f32_e32 v24, v24, v25
	ds_bpermute_b32 v25, v218, v24
	s_waitcnt lgkmcnt(0)
	v_add_f32_e32 v24, v24, v25
	ds_bpermute_b32 v25, v219, v24
	s_waitcnt lgkmcnt(0)
	v_add_f32_e32 v24, v24, v25
	ds_bpermute_b32 v25, v220, v24
	s_waitcnt lgkmcnt(0)
	v_add_f32_e32 v24, v24, v25
	ds_bpermute_b32 v25, v221, v24
	s_waitcnt lgkmcnt(0)
	v_add_f32_e32 v60, v24, v25
	ds_bpermute_b32 v61, v222, v60
	global_load_dwordx4 v[24:27], v[56:57], off offset:16
	global_load_dwordx4 v[28:31], v[56:57], off
	global_load_dwordx4 v[32:35], v[58:59], off offset:16
	global_load_dwordx4 v[36:39], v[58:59], off
	s_waitcnt lgkmcnt(0)
	v_add_f32_e32 v60, v60, v61
	v_mul_f32_e32 v60, 0x3a000000, v60
	v_add_f32_e64 v62, v22, -v60
	v_add_f32_e64 v63, v23, -v60
	v_add_f32_e64 v42, v42, -v60
	v_add_f32_e64 v43, v43, -v60
	v_add_f32_e64 v72, v44, -v60
	v_add_f32_e64 v73, v45, -v60
	v_mul_f32_e64 v44, v62, v62
	v_mul_f32_e64 v45, v63, v63
	v_add_f32_e64 v76, v46, -v60
	v_add_f32_e64 v77, v47, -v60
	v_mul_f32_e64 v46, v42, v42
	v_mul_f32_e64 v47, v43, v43
	v_add_f32_e32 v44, v44, v45
	v_add_f32_e64 v64, v14, -v60
	v_add_f32_e64 v65, v15, -v60
	v_add_f32_e32 v44, v46, v44
	v_add_f32_e64 v22, v48, -v60
	v_add_f32_e64 v23, v49, -v60
	v_mul_f32_e64 v48, v64, v64
	v_mul_f32_e64 v49, v65, v65
	v_add_f32_e32 v44, v47, v44
	v_add_f32_e64 v66, v16, -v60
	v_add_f32_e64 v67, v17, -v60
	v_add_f32_e32 v44, v48, v44
	v_mul_f32_e64 v78, v66, v66
	v_mul_f32_e64 v79, v67, v67
	v_add_f32_e32 v44, v49, v44
	v_add_f32_e64 v68, v10, -v60
	v_add_f32_e64 v69, v11, -v60
	v_add_f32_e32 v44, v78, v44
	v_mul_f32_e64 v80, v68, v68
	v_mul_f32_e64 v81, v69, v69
	v_add_f32_e32 v44, v79, v44
	v_add_f32_e64 v70, v12, -v60
	v_add_f32_e64 v71, v13, -v60
	v_add_f32_e32 v44, v80, v44
	v_mul_f32_e64 v82, v70, v70
	v_mul_f32_e64 v83, v71, v71
	v_add_f32_e32 v44, v81, v44
	v_add_f32_e32 v44, v82, v44
	v_mul_f32_e64 v84, v72, v72
	v_mul_f32_e64 v85, v73, v73
	v_add_f32_e32 v44, v83, v44
	v_add_f32_e32 v44, v84, v44
	v_mul_f32_e64 v86, v76, v76
	v_mul_f32_e64 v87, v77, v77
	v_add_f32_e32 v44, v85, v44
	v_add_f32_e32 v44, v86, v44
	v_mul_f32_e64 v88, v22, v22
	v_mul_f32_e64 v89, v23, v23
	v_add_f32_e32 v44, v87, v44
	v_add_f32_e64 v90, v50, -v60
	v_add_f32_e64 v91, v51, -v60
	v_add_f32_e32 v44, v88, v44
	v_mul_f32_e64 v50, v90, v90
	v_mul_f32_e64 v51, v91, v91
	v_add_f32_e32 v44, v89, v44
	v_add_f32_e64 v52, v52, -v60
	v_add_f32_e64 v53, v53, -v60
	v_add_f32_e32 v44, v50, v44
	v_mul_f32_e64 v92, v52, v52
	v_mul_f32_e64 v93, v53, v53
	v_add_f32_e32 v44, v51, v44
	v_add_f32_e64 v54, v54, -v60
	v_add_f32_e64 v55, v55, -v60
	v_add_f32_e32 v44, v92, v44
	v_mul_f32_e64 v94, v54, v54
	v_mul_f32_e64 v95, v55, v55
	v_add_f32_e32 v44, v93, v44
	v_add_f32_e64 v14, v18, -v60
	v_add_f32_e64 v15, v19, -v60
	v_add_f32_e32 v44, v94, v44
	v_mul_f32_e64 v18, v14, v14
	v_mul_f32_e64 v19, v15, v15
	v_add_f32_e32 v44, v95, v44
	v_add_f32_e64 v16, v20, -v60
	v_add_f32_e64 v17, v21, -v60
	v_add_f32_e32 v18, v18, v44
	v_mul_f32_e64 v20, v16, v16
	v_mul_f32_e64 v21, v17, v17
	v_add_f32_e32 v18, v19, v18
	v_add_f32_e64 v10, v74, -v60
	v_add_f32_e64 v11, v75, -v60
	v_add_f32_e32 v18, v20, v18
	v_mul_f32_e64 v74, v10, v10
	v_mul_f32_e64 v75, v11, v11
	v_add_f32_e32 v18, v21, v18
	v_add_f32_e64 v12, v40, -v60
	v_add_f32_e64 v13, v41, -v60
	v_add_f32_e32 v18, v74, v18
	v_mul_f32_e64 v40, v12, v12
	v_mul_f32_e64 v41, v13, v13
	v_add_f32_e32 v18, v75, v18
	v_add_f32_e32 v18, v40, v18
	v_add_f32_e32 v18, v41, v18
	ds_bpermute_b32 v19, v217, v18
	s_waitcnt lgkmcnt(0)
	v_add_f32_e32 v18, v18, v19
	ds_bpermute_b32 v19, v218, v18
	s_waitcnt lgkmcnt(0)
	v_add_f32_e32 v18, v18, v19
	ds_bpermute_b32 v19, v219, v18
	s_waitcnt lgkmcnt(0)
	v_add_f32_e32 v18, v18, v19
	ds_bpermute_b32 v19, v220, v18
	s_waitcnt lgkmcnt(0)
	v_add_f32_e32 v18, v18, v19
	ds_bpermute_b32 v19, v221, v18
	s_waitcnt lgkmcnt(0)
	v_add_f32_e32 v18, v18, v19
	ds_bpermute_b32 v19, v222, v18
	s_waitcnt lgkmcnt(0)
	v_add_f32_e32 v18, v18, v19
	v_mov_b32_e32 v226, 0x3727c5ac
	v_fmamk_f32 v18, v18, 0x3a000000, v226
	v_mul_f32_e32 v19, 0x4b800000, v18
	v_cmp_gt_f32_e32 vcc, s63, v18
	s_nop 1
	v_cndmask_b32_e32 v18, v18, v19, vcc
	v_rsq_f32_e32 v18, v18
	s_nop 0
	v_mul_f32_e32 v19, 0x45800000, v18
	v_cndmask_b32_e32 v20, v18, v19, vcc
	v_mul_f32_e64 v18, v62, v20
	v_mul_f32_e64 v19, v63, v20
	v_mul_f32_e64 v40, v42, v20
	v_mul_f32_e64 v41, v43, v20
	v_mul_f32_e64 v42, v64, v20
	v_mul_f32_e64 v43, v65, v20
	v_mul_f32_e64 v44, v66, v20
	v_mul_f32_e64 v45, v67, v20
	s_waitcnt vmcnt(0)
	v_fma_f32 v28, v28, v18, v36
	v_fma_f32 v29, v29, v19, v37
	v_fma_f32 v30, v30, v40, v38
	v_fma_f32 v31, v31, v41, v39
	v_fma_f32 v32, v24, v42, v32
	v_fma_f32 v33, v25, v43, v33
	v_add_co_u32_e32 v24, vcc, s65, v8
	v_fma_f32 v34, v26, v44, v34
	v_fma_f32 v35, v27, v45, v35
	global_store_dwordx4 v[4:5], v[28:31], off
	global_store_dwordx4 v[4:5], v[32:35], off offset:16
	v_addc_co_u32_e32 v25, vcc, 0, v9, vcc
	global_load_dwordx4 v[36:39], v[24:25], off offset:-4096
	v_lshl_add_u64 v[18:19], v[8:9], 0, s[26:27]
	global_load_dwordx4 v[40:43], v[18:19], off offset:16
	global_load_dwordx4 v[44:47], v[8:9], off
	global_load_dwordx4 v[48:51], v[8:9], off offset:16
	v_lshl_add_u64 v[18:19], v[0:1], 1, s[48:49]
	v_mul_f32_e64 v22, v22, v20
	v_mul_f32_e64 v23, v23, v20
	v_mul_f32_e64 v10, v10, v20
	v_mul_f32_e64 v11, v11, v20
	v_mul_f32_e64 v12, v12, v20
	v_mul_f32_e64 v13, v13, v20
	s_waitcnt vmcnt(3)
	v_add_f32_e64 v26, v36, 1.0
	v_add_f32_e64 v27, v37, 1.0
	v_add_f32_e64 v36, v38, 1.0
	v_add_f32_e64 v37, v39, 1.0
	s_waitcnt vmcnt(2)
	v_add_f32_e64 v38, v40, 1.0
	v_add_f32_e64 v39, v41, 1.0
	v_add_f32_e64 v40, v42, 1.0
	v_add_f32_e64 v41, v43, 1.0
	s_waitcnt vmcnt(1)
; DI unsigned pk2(float a, float b) { f32x2 v = {a, b}; bf2_t r = __builtin_convertvector(v, bf2_t); return __builtin_bit_cast(unsigned, r); }
; __device__ __forceinline__ void phase_expert(const Params& p, int layer, int row0) {
;     ...
; #pragma unroll
;     for (int c = 0; c < 2; ++c) {
; #pragma unroll
;       for (int q8 = 0; q8 < 2; ++q8) {
;         const int col = c * 1024 + lane2 * 16 + q8 * 8;
;         float o[8];
; #pragma unroll
;         for (int e = 0; e < 8; ++e) o[e] = (pre[c * 16 + q8 * 8 + e] - mu) * rstd * G[col + e] + B[col + e];
;         if (layer == 0) {
;           *(f32x4*)(XR + (size_t)row * LDF + col) = f32x4{o[0], o[1], o[2], o[3]};
;           *(f32x4*)(XR + (size_t)row * LDF + col + 4) = f32x4{o[4], o[5], o[6], o[7]};
;           float z[8];
; #pragma unroll
;           for (int e = 0; e < 8; ++e) z[e] = o[e] * (1.f + mdn[2048 + col + e]) + mdn[col + e];
;           *(u32x4*)(XMo + (size_t)row * LDX + col) = u32x4{pk2(z[0], z[1]), pk2(z[2], z[3]), pk2(z[4], z[5]), pk2(z[6], z[7])};
	v_fma_f32 v26, v26, v28, v44
	v_fma_f32 v27, v27, v29, v45
	v_fma_f32 v28, v36, v30, v46
	v_fma_f32 v29, v37, v31, v47
	s_waitcnt vmcnt(0)
	v_fma_f32 v30, v38, v32, v48
	v_fma_f32 v31, v39, v33, v49
	v_fma_f32 v32, v40, v34, v50
	v_fma_f32 v33, v41, v35, v51
	v_cvt_pk_bf16_f32 v26, v26, v27
	v_cvt_pk_bf16_f32 v27, v28, v29
	v_cvt_pk_bf16_f32 v28, v30, v31
	v_cvt_pk_bf16_f32 v29, v32, v33
	global_store_dwordx4 v[18:19], v[26:29], off
	global_load_dwordx4 v[26:29], v[58:59], off offset:32
	s_nop 0
	global_load_dwordx4 v[30:33], v[56:57], off offset:32
	global_load_dwordx4 v[34:37], v[56:57], off offset:48
	global_load_dwordx4 v[38:41], v[58:59], off offset:48
	v_mul_f32_e64 v44, v68, v20
	v_mul_f32_e64 v45, v69, v20
	v_mul_f32_e64 v46, v70, v20
	v_mul_f32_e64 v47, v71, v20
	v_add_co_u32_e32 v42, vcc, s64, v8
	v_mul_f32_e64 v48, v72, v20
	v_mul_f32_e64 v49, v73, v20
	v_mul_f32_e64 v50, v76, v20
	v_mul_f32_e64 v51, v77, v20
	v_addc_co_u32_e32 v43, vcc, 0, v9, vcc
	v_add_co_u32_e32 v56, vcc, s61, v56
	s_waitcnt vmcnt(2)
	v_fma_f32 v26, v30, v44, v26
	v_fma_f32 v27, v31, v45, v27
	v_fma_f32 v28, v32, v46, v28
	v_fma_f32 v29, v33, v47, v29
	s_waitcnt vmcnt(0)
	v_fma_f32 v30, v34, v48, v38
	v_fma_f32 v31, v35, v49, v39
	v_fma_f32 v32, v36, v50, v40
	v_fma_f32 v33, v37, v51, v41
	global_store_dwordx4 v[4:5], v[26:29], off offset:32
	global_store_dwordx4 v[4:5], v[30:33], off offset:48
	global_load_dwordx4 v[34:37], v[42:43], off offset:32
	v_lshl_add_u64 v[38:39], v[8:9], 0, s[28:29]
	global_load_dwordx4 v[38:41], v[38:39], off offset:16
	s_nop 0
	global_load_dwordx4 v[42:45], v[8:9], off offset:32
	global_load_dwordx4 v[46:49], v[8:9], off offset:48
	v_add_u32_e32 v50, 0x402, v0
	v_ashrrev_i32_e32 v51, 31, v50
	v_addc_co_u32_e32 v57, vcc, 0, v57, vcc
	v_lshlrev_b64 v[50:51], 2, v[50:51]
	v_add_co_u32_e32 v58, vcc, s61, v58
	v_lshl_add_u64 v[60:61], s[42:43], 0, v[50:51]
	v_lshl_add_u64 v[62:63], s[44:45], 0, v[50:51]
	v_addc_co_u32_e32 v59, vcc, 0, v59, vcc
	v_add_u32_e32 v0, 0x40a, v0
	v_ashrrev_i32_e32 v1, 31, v0
	s_waitcnt vmcnt(3)
	v_add_f32_e64 v34, v34, 1.0
	v_add_f32_e64 v35, v35, 1.0
	v_add_f32_e64 v36, v36, 1.0
	v_add_f32_e64 v37, v37, 1.0
	s_waitcnt vmcnt(2)
	v_add_f32_e64 v38, v38, 1.0
	v_add_f32_e64 v39, v39, 1.0
	v_add_f32_e64 v40, v40, 1.0
	v_add_f32_e64 v41, v41, 1.0
	s_waitcnt vmcnt(1)
	v_fma_f32 v26, v34, v26, v42
	v_fma_f32 v27, v35, v27, v43
	v_fma_f32 v28, v36, v28, v44
	v_fma_f32 v29, v37, v29, v45
	s_waitcnt vmcnt(0)
	v_fma_f32 v30, v38, v30, v46
	v_fma_f32 v31, v39, v31, v47
	v_fma_f32 v32, v32, v40, v48
	v_fma_f32 v33, v33, v41, v49
	v_cvt_pk_bf16_f32 v26, v26, v27
	v_cvt_pk_bf16_f32 v27, v28, v29
	v_cvt_pk_bf16_f32 v28, v30, v31
	v_cvt_pk_bf16_f32 v29, v32, v33
	global_store_dwordx4 v[18:19], v[26:29], off offset:16
	global_load_dwordx2 v[34:35], v[56:57], off
	global_load_dwordx2 v[36:37], v[58:59], off
	s_nop 0
	global_load_dwordx4 v[26:29], v[62:63], off
	global_load_dwordx4 v[30:33], v[60:61], off
	global_load_dwordx2 v[38:39], v[60:61], off offset:16
	global_load_dwordx2 v[40:41], v[62:63], off offset:16
	v_mul_f32_e64 v44, v90, v20
	v_mul_f32_e64 v45, v91, v20
	v_lshl_add_u64 v[46:47], s[0:1], 0, v[50:51]
	v_mul_f32_e64 v48, v52, v20
	v_mul_f32_e64 v49, v53, v20
	v_mul_f32_e64 v50, v54, v20
	v_mul_f32_e64 v51, v55, v20
	v_lshl_add_u64 v[42:43], v[8:9], 0, s[30:31]
	s_waitcnt vmcnt(4)
	v_fma_f32 v34, v22, v34, v36
	v_fma_f32 v35, v23, v35, v37
	v_add_co_u32_e32 v22, vcc, s61, v8
	s_waitcnt vmcnt(2)
; DI unsigned pk2(float a, float b) { f32x2 v = {a, b}; bf2_t r = __builtin_convertvector(v, bf2_t); return __builtin_bit_cast(unsigned, r); }
; __device__ __forceinline__ void phase_expert(const Params& p, int layer, int row0) {
;     ...
; #pragma unroll
;     for (int c = 0; c < 2; ++c) {
; #pragma unroll
;       for (int q8 = 0; q8 < 2; ++q8) {
;         const int col = c * 1024 + lane2 * 16 + q8 * 8;
;         float o[8];
; #pragma unroll
;         for (int e = 0; e < 8; ++e) o[e] = (pre[c * 16 + q8 * 8 + e] - mu) * rstd * G[col + e] + B[col + e];
;         if (layer == 0) {
;           *(f32x4*)(XR + (size_t)row * LDF + col) = f32x4{o[0], o[1], o[2], o[3]};
;           *(f32x4*)(XR + (size_t)row * LDF + col + 4) = f32x4{o[4], o[5], o[6], o[7]};
;           float z[8];
; #pragma unroll
;           for (int e = 0; e < 8; ++e) z[e] = o[e] * (1.f + mdn[2048 + col + e]) + mdn[col + e];
;           *(u32x4*)(XMo + (size_t)row * LDX + col) = u32x4{pk2(z[0], z[1]), pk2(z[2], z[3]), pk2(z[4], z[5]), pk2(z[6], z[7])};
	v_fma_f32 v36, v44, v30, v26
	v_fma_f32 v37, v45, v31, v27
	v_fma_f32 v26, v48, v32, v28
	v_fma_f32 v27, v49, v33, v29
	s_waitcnt vmcnt(0)
	v_fma_f32 v28, v50, v38, v40
	v_fma_f32 v29, v51, v39, v41
	global_store_dwordx4 v[2:3], v[34:37], off
	global_store_dwordx4 v[6:7], v[26:29], off offset:16
	global_load_dwordx4 v[30:33], v[24:25], off
	global_load_dwordx4 v[38:41], v[42:43], off offset:16
	v_addc_co_u32_e32 v23, vcc, 0, v9, vcc
	global_load_dwordx2 v[6:7], v[22:23], off
	global_load_dwordx4 v[42:45], v[46:47], off
	s_nop 0
	global_load_dwordx2 v[46:47], v[46:47], off offset:16
	v_lshlrev_b64 v[48:49], 2, v[0:1]
	v_lshl_add_u64 v[0:1], s[42:43], 0, v[48:49]
	v_lshl_add_u64 v[50:51], s[44:45], 0, v[48:49]
	v_lshl_add_u64 v[8:9], v[8:9], 0, s[36:37]
	v_cmp_lt_i32_e32 vcc, s66, v215
	s_or_b64 s[4:5], vcc, s[4:5]
	s_waitcnt vmcnt(4)
	v_add_f32_e64 v30, v30, 1.0
	v_add_f32_e64 v31, v31, 1.0
	v_add_f32_e64 v32, v32, 1.0
	v_add_f32_e64 v33, v33, 1.0
	s_waitcnt vmcnt(3)
	v_add_f32_e64 v38, v38, 1.0
	v_add_f32_e64 v39, v39, 1.0
	v_add_f32_e64 v40, v40, 1.0
	v_add_f32_e64 v41, v41, 1.0
	s_waitcnt vmcnt(2)
	v_fma_f32 v6, v34, v30, v6
	v_fma_f32 v7, v35, v31, v7
	s_waitcnt vmcnt(1)
	v_fma_f32 v30, v36, v32, v42
	v_fma_f32 v31, v37, v33, v43
	v_fma_f32 v32, v26, v38, v44
	v_fma_f32 v33, v27, v39, v45
	s_waitcnt vmcnt(0)
	v_fma_f32 v34, v28, v40, v46
	v_fma_f32 v35, v29, v41, v47
	v_cvt_pk_bf16_f32 v26, v6, v7
	v_cvt_pk_bf16_f32 v27, v30, v31
	v_cvt_pk_bf16_f32 v28, v32, v33
	v_cvt_pk_bf16_f32 v29, v34, v35
	global_store_dwordx4 v[18:19], v[26:29], off offset:2048
	global_load_dwordx2 v[6:7], v[56:57], off offset:32
	global_load_dwordx2 v[34:35], v[58:59], off offset:32
	s_nop 0
	global_load_dwordx4 v[26:29], v[50:51], off
	global_load_dwordx4 v[30:33], v[0:1], off
	s_nop 0
	global_load_dwordx2 v[0:1], v[0:1], off offset:16
	s_nop 0
	global_load_dwordx2 v[36:37], v[50:51], off offset:16
	v_lshl_add_u64 v[38:39], v[4:5], 0, s[22:23]
	v_mul_f32_e64 v4, v14, v20
	v_mul_f32_e64 v5, v15, v20
	v_mul_f32_e64 v14, v16, v20
	v_mul_f32_e64 v15, v17, v20
	s_waitcnt vmcnt(4)
	v_fma_f32 v4, v4, v6, v34
	v_fma_f32 v5, v5, v7, v35
	s_waitcnt vmcnt(2)
	v_fma_f32 v6, v14, v30, v26
	v_fma_f32 v7, v15, v31, v27
	v_fma_f32 v10, v10, v32, v28
	v_fma_f32 v11, v11, v33, v29
	s_waitcnt vmcnt(0)
	v_fma_f32 v12, v12, v0, v36
	v_fma_f32 v13, v13, v1, v37
	global_store_dwordx4 v[2:3], v[4:7], off offset:32
	global_store_dwordx4 v[38:39], v[10:13], off offset:16
	global_load_dwordx4 v[0:3], v[24:25], off offset:32
	s_nop 0
	global_load_dwordx4 v[14:17], v[8:9], off offset:16
	v_lshl_add_u64 v[8:9], s[0:1], 0, v[48:49]
	global_load_dwordx2 v[24:25], v[22:23], off offset:32
	s_nop 0
	global_load_dwordx4 v[20:23], v[8:9], off
	s_nop 0
	global_load_dwordx2 v[8:9], v[8:9], off offset:16
	s_waitcnt vmcnt(4)
	v_add_f32_e64 v0, v0, 1.0
	v_add_f32_e64 v1, v1, 1.0
	v_add_f32_e64 v2, v2, 1.0
	v_add_f32_e64 v3, v3, 1.0
	s_waitcnt vmcnt(3)
	v_add_f32_e64 v14, v14, 1.0
	v_add_f32_e64 v15, v15, 1.0
	v_add_f32_e64 v16, v16, 1.0
	v_add_f32_e64 v17, v17, 1.0
	s_waitcnt vmcnt(2)
	v_fma_f32 v0, v4, v0, v24
	v_fma_f32 v1, v5, v1, v25
	s_waitcnt vmcnt(1)
	v_fma_f32 v2, v6, v2, v20
	v_fma_f32 v3, v7, v3, v21
	v_fma_f32 v4, v10, v14, v22
	v_fma_f32 v5, v11, v15, v23
	s_waitcnt vmcnt(0)
	v_fma_f32 v6, v12, v16, v8
	v_fma_f32 v7, v13, v17, v9
	v_cvt_pk_bf16_f32 v0, v0, v1
	v_cvt_pk_bf16_f32 v1, v2, v3
	v_cvt_pk_bf16_f32 v2, v4, v5
	v_cvt_pk_bf16_f32 v3, v6, v7
	global_store_dwordx4 v[18:19], v[0:3], off offset:2064
	s_andn2_b64 exec, exec, s[4:5]
	s_cbranch_execnz .LBB0_1932

; __device__ __forceinline__ void phase_expert(const Params& p, int layer, int row0) {
;     ...
;     for (int i0 = 0; i0 < 128; i0 += 4) {
;       u32x4 ua[4]; u32x2 ub[4];
;       float gk[4];
;       int ek[4];
; #pragma unroll
;       for (int k = 0; k < 4; ++k) {
;         ek[k] = __builtin_amdgcn_readfirstlane(ex[i0 + k]);
;         gk[k] = gt[i0 + k];
;         const unsigned char* up = UB + (size_t)ek[k] * 1536;
;         ua[k] = *(const u32x4*)(up + lane * 16); ub[k] = *(const u32x2*)(up + 1024 + lane * 8);
;       }
;       float dk[4];
; #pragma unroll
;       for (int k = 0; k < 4; ++k) {
;         const u32x6 pk = {ua[k][0], ua[k][1], ua[k][2], ua[k][3], ub[k][0], ub[k][1]};
;         const f32x32 f = __builtin_amdgcn_cvt_scalef32_pk32_f32_fp6(pk, 1.0f);
;         float d0 = 0.f, d1 = 0.f;
; #pragma unroll
;         for (int j = 0; j < 32; j += 2) { d0 += f[j] * u[j]; d1 += f[j + 1] * u[j + 1]; }
;         dk[k] = d0 + d1;
;         __builtin_amdgcn_sched_barrier(0);
;       }
; #pragma unroll
;       for (int k = 0; k < 4; ++k) {
;         const unsigned char* vp = VB + (size_t)ek[k] * 1536;
;         ua[k] = *(const u32x4*)(vp + lane * 16); ub[k] = *(const u32x2*)(vp + 1024 + lane * 8);
;       }
.LBB0_2561:
	s_add_u32 s98, s28, 16
	s_addc_u32 s99, s29, 0
	s_cmp_ge_i32 s42, 0x78
	s_cselect_b32 s98, s28, s98
	s_cselect_b32 s99, s29, s99
	global_load_dwordx4 v[252:255], v139, s[98:99]
	global_load_dwordx4 v[134:137], v222, s[28:29]
	s_waitcnt vmcnt(8)
	v_cvt_scalef32_pk32_f32_fp6 v[0:31], v[226:231], 1.0
	v_fma_f32 v0, v0, v150, 0
	v_fma_f32 v1, v1, v151, 0
	v_fma_f32 v0, v2, v152, v0
	v_fma_f32 v1, v3, v153, v1
	v_fma_f32 v0, v4, v154, v0
	v_fma_f32 v1, v5, v155, v1
	v_fma_f32 v0, v6, v156, v0
	v_fma_f32 v1, v7, v157, v1
	v_fma_f32 v0, v8, v144, v0
	v_fma_f32 v1, v9, v145, v1
	v_fma_f32 v0, v10, v146, v0
	v_fma_f32 v1, v11, v147, v1
	v_fma_f32 v0, v12, v148, v0
	v_fma_f32 v1, v13, v149, v1
	v_fma_f32 v0, v14, v158, v0
	v_fma_f32 v1, v15, v159, v1
	v_fma_f32 v0, v16, v160, v0
	v_fma_f32 v1, v17, v161, v1
	v_fma_f32 v0, v18, v166, v0
	v_fma_f32 v1, v19, v167, v1
	v_fma_f32 v0, v20, v170, v0
	v_fma_f32 v1, v21, v171, v1
	v_fma_f32 v0, v22, v174, v0
	v_fma_f32 v1, v23, v175, v1
	v_fma_f32 v0, v24, v164, v0
	v_fma_f32 v1, v25, v165, v1
	v_fma_f32 v0, v26, v168, v0
	v_fma_f32 v1, v27, v169, v1
	v_fma_f32 v0, v28, v172, v0
	v_fma_f32 v1, v29, v173, v1
	v_fma_f32 v56, v30, v176, v0
	v_fma_f32 v57, v31, v177, v1
	s_waitcnt vmcnt(6)
	v_cvt_scalef32_pk32_f32_fp6 v[0:31], v[232:237], 1.0
	v_fma_f32 v0, v0, v150, 0
	v_fma_f32 v1, v1, v151, 0
	v_fma_f32 v0, v2, v152, v0
	v_fma_f32 v1, v3, v153, v1
	v_fma_f32 v0, v4, v154, v0
	v_fma_f32 v1, v5, v155, v1
	v_fma_f32 v0, v6, v156, v0
	v_fma_f32 v1, v7, v157, v1
	v_fma_f32 v0, v8, v144, v0
	v_fma_f32 v1, v9, v145, v1
	v_fma_f32 v0, v10, v146, v0
	v_fma_f32 v1, v11, v147, v1
	v_fma_f32 v0, v12, v148, v0
	v_fma_f32 v1, v13, v149, v1
	v_fma_f32 v0, v14, v158, v0
	v_fma_f32 v1, v15, v159, v1
	v_fma_f32 v0, v16, v160, v0
	v_fma_f32 v1, v17, v161, v1
	v_fma_f32 v0, v18, v166, v0
	v_fma_f32 v1, v19, v167, v1
	v_fma_f32 v0, v20, v170, v0
	v_fma_f32 v1, v21, v171, v1
	v_fma_f32 v0, v22, v174, v0
	v_fma_f32 v1, v23, v175, v1
	v_fma_f32 v0, v24, v164, v0
	v_fma_f32 v1, v25, v165, v1
	v_fma_f32 v0, v26, v168, v0
	v_fma_f32 v1, v27, v169, v1
	v_fma_f32 v0, v28, v172, v0
	v_fma_f32 v1, v29, v173, v1
	v_fma_f32 v58, v30, v176, v0
	v_fma_f32 v59, v31, v177, v1
	s_waitcnt vmcnt(4)
	v_cvt_scalef32_pk32_f32_fp6 v[0:31], v[240:245], 1.0
	v_fma_f32 v0, v0, v150, 0
	v_fma_f32 v1, v1, v151, 0
	v_fma_f32 v0, v2, v152, v0
	v_fma_f32 v1, v3, v153, v1
	v_fma_f32 v0, v4, v154, v0
	v_fma_f32 v1, v5, v155, v1
	v_fma_f32 v0, v6, v156, v0
	v_fma_f32 v1, v7, v157, v1
	v_fma_f32 v0, v8, v144, v0
	v_fma_f32 v1, v9, v145, v1
	v_fma_f32 v0, v10, v146, v0
	v_fma_f32 v1, v11, v147, v1
	v_fma_f32 v0, v12, v148, v0
	v_fma_f32 v1, v13, v149, v1
	v_fma_f32 v0, v14, v158, v0
	v_fma_f32 v1, v15, v159, v1
	v_fma_f32 v0, v16, v160, v0
	v_fma_f32 v1, v17, v161, v1
	v_fma_f32 v0, v18, v166, v0
	v_fma_f32 v1, v19, v167, v1
	v_fma_f32 v0, v20, v170, v0
	v_fma_f32 v1, v21, v171, v1
	v_fma_f32 v0, v22, v174, v0
	v_fma_f32 v1, v23, v175, v1
	v_fma_f32 v0, v24, v164, v0
	v_fma_f32 v1, v25, v165, v1
	v_fma_f32 v0, v26, v168, v0
	v_fma_f32 v1, v27, v169, v1
	v_fma_f32 v0, v28, v172, v0
	v_fma_f32 v1, v29, v173, v1
	v_fma_f32 v96, v30, v176, v0
	v_fma_f32 v97, v31, v177, v1
	s_waitcnt vmcnt(2)
	v_cvt_scalef32_pk32_f32_fp6 v[0:31], v[246:251], 1.0
	v_fma_f32 v0, v0, v150, 0
	v_fma_f32 v1, v1, v151, 0
	v_fma_f32 v0, v2, v152, v0
	v_fma_f32 v1, v3, v153, v1
	v_fma_f32 v0, v4, v154, v0
	v_fma_f32 v1, v5, v155, v1
	v_fma_f32 v0, v6, v156, v0
	v_fma_f32 v1, v7, v157, v1
	v_fma_f32 v0, v8, v144, v0
	v_fma_f32 v1, v9, v145, v1
	v_fma_f32 v0, v10, v146, v0
	v_fma_f32 v1, v11, v147, v1
	v_fma_f32 v0, v12, v148, v0
	v_fma_f32 v1, v13, v149, v1
	v_fma_f32 v0, v14, v158, v0
	v_fma_f32 v1, v15, v159, v1
	v_fma_f32 v0, v16, v160, v0
	v_fma_f32 v1, v17, v161, v1
	v_fma_f32 v0, v18, v166, v0
	v_fma_f32 v1, v19, v167, v1
	v_fma_f32 v0, v20, v170, v0
	v_fma_f32 v1, v21, v171, v1
	v_fma_f32 v0, v22, v174, v0
	v_fma_f32 v1, v23, v175, v1
	v_fma_f32 v0, v24, v164, v0
	v_fma_f32 v1, v25, v165, v1
	v_fma_f32 v0, v26, v168, v0
	v_fma_f32 v1, v27, v169, v1
	v_fma_f32 v0, v28, v172, v0
	v_fma_f32 v1, v29, v173, v1
	v_fma_f32 v208, v30, v176, v0
	v_fma_f32 v209, v31, v177, v1
	s_add_u32 s48, s17, s44
	s_addc_u32 s49, s23, 0
	v_lshl_add_u64 v[0:1], s[48:49], 0, v[138:139]
	v_lshl_add_u64 v[2:3], s[48:49], 0, v[142:143]
	global_load_dwordx4 v[32:35], v[0:1], off
	global_load_dwordx2 v[36:37], v[2:3], off offset:1024
	s_add_u32 s48, s17, s27
	s_addc_u32 s49, s23, 0
	v_lshl_add_u64 v[0:1], s[48:49], 0, v[138:139]
	v_lshl_add_u64 v[2:3], s[48:49], 0, v[142:143]
	global_load_dwordx4 v[38:41], v[0:1], off
	global_load_dwordx2 v[42:43], v[2:3], off offset:1024
	s_add_u32 s48, s17, s45
	s_addc_u32 s49, s23, 0
	v_lshl_add_u64 v[0:1], s[48:49], 0, v[138:139]
	v_lshl_add_u64 v[2:3], s[48:49], 0, v[142:143]
	global_load_dwordx4 v[98:101], v[0:1], off
	global_load_dwordx2 v[102:103], v[2:3], off offset:1024
	s_add_u32 s48, s17, s47
	s_addc_u32 s49, s23, 0
	v_lshl_add_u64 v[0:1], s[48:49], 0, v[138:139]
	v_lshl_add_u64 v[2:3], s[48:49], 0, v[142:143]
	global_load_dwordx4 v[128:131], v[0:1], off
	global_load_dwordx2 v[132:133], v[2:3], off offset:1024
	s_waitcnt vmcnt(9)
; __device__ __forceinline__ void phase_expert(const Params& p, int layer, int row0) {
;     ...
; #pragma unroll
;       for (int k = 0; k < 4; ++k) {
;         ek[k] = __builtin_amdgcn_readfirstlane(ex[i0 + k]);
;         gk[k] = gt[i0 + k];
;         const unsigned char* up = UB + (size_t)ek[k] * 1536;
;         ua[k] = *(const u32x4*)(up + lane * 16); ub[k] = *(const u32x2*)(up + 1024 + lane * 8);
;     ...
; #pragma unroll
;       for (int o = 32; o >= 1; o >>= 1) {
; #pragma unroll
;         for (int k = 0; k < 4; ++k) dk[k] += __shfl_xor(dk[k], o);
;       }
; #pragma unroll
;       for (int k = 0; k < 4; ++k) {
;         const float a = dk[k] * (1.f / SC_U);
;         const float w = gk[k] * (0.5f * a * (1.f + my_erf(a * 0.7071067811865476f)));
;         const u32x6 pk = {ua[k][0], ua[k][1], ua[k][2], ua[k][3], ub[k][0], ub[k][1]};
;         const f32x32 f = __builtin_amdgcn_cvt_scalef32_pk32_f32_fp6(pk, 1.0f);
; #pragma unroll
;         for (int j = 0; j < 32; ++j) y[j] += w * f[j];
;         __builtin_amdgcn_sched_barrier(0);
;       }
	v_readfirstlane_b32 s44, v252
	v_readfirstlane_b32 s27, v253
	v_readfirstlane_b32 s45, v254
	v_readfirstlane_b32 s47, v255
	s_mulk_i32 s44, 0x600
	s_mulk_i32 s27, 0x600
	s_mulk_i32 s45, 0x600
	s_mulk_i32 s47, 0x600
	s_add_u32 s48, s11, s44
	s_addc_u32 s49, s13, 0
	v_lshl_add_u64 v[0:1], s[48:49], 0, v[138:139]
	v_lshl_add_u64 v[2:3], s[48:49], 0, v[142:143]
	global_load_dwordx4 v[226:229], v[0:1], off
	global_load_dwordx2 v[230:231], v[2:3], off offset:1024
	s_add_u32 s48, s11, s27
	s_addc_u32 s49, s13, 0
	v_lshl_add_u64 v[0:1], s[48:49], 0, v[138:139]
	v_lshl_add_u64 v[2:3], s[48:49], 0, v[142:143]
	global_load_dwordx4 v[232:235], v[0:1], off
	global_load_dwordx2 v[236:237], v[2:3], off offset:1024
	s_add_u32 s48, s11, s45
	s_addc_u32 s49, s13, 0
	v_lshl_add_u64 v[0:1], s[48:49], 0, v[138:139]
	v_lshl_add_u64 v[2:3], s[48:49], 0, v[142:143]
	global_load_dwordx4 v[240:243], v[0:1], off
	global_load_dwordx2 v[244:245], v[2:3], off offset:1024
	s_add_u32 s48, s11, s47
	s_addc_u32 s49, s13, 0
	v_lshl_add_u64 v[0:1], s[48:49], 0, v[138:139]
	v_lshl_add_u64 v[2:3], s[48:49], 0, v[142:143]
	global_load_dwordx4 v[246:249], v[0:1], off
	global_load_dwordx2 v[250:251], v[2:3], off offset:1024
	s_waitcnt vmcnt(14)
	v_cvt_scalef32_pk32_f32_fp6 v[0:31], v[32:37], 1.0
	v_mov_b32_e32 v32, v59
	v_mov_b32_e32 v33, v57
	v_mov_b32_e32 v59, v56
	v_add_f32_e64 v32, v32, v58
	v_add_f32_e64 v33, v33, v59
	ds_bpermute_b32 v35, v216, v33
	ds_bpermute_b32 v34, v216, v32
	s_waitcnt vmcnt(12)
	v_cvt_scalef32_pk32_f32_fp6 v[64:95], v[38:43], 1.0
	s_waitcnt lgkmcnt(0)
	v_add_f32_e64 v32, v32, v34
	v_add_f32_e64 v33, v33, v35
	ds_bpermute_b32 v35, v217, v33
	ds_bpermute_b32 v34, v217, v32
	s_waitcnt lgkmcnt(0)
	v_add_f32_e64 v32, v32, v34
	v_add_f32_e64 v33, v33, v35
	ds_bpermute_b32 v35, v218, v33
	ds_bpermute_b32 v34, v218, v32
	s_waitcnt lgkmcnt(0)
	v_add_f32_e64 v32, v32, v34
	v_add_f32_e64 v33, v33, v35
	ds_bpermute_b32 v35, v219, v33
	ds_bpermute_b32 v34, v219, v32
	s_waitcnt lgkmcnt(0)
	v_add_f32_e64 v32, v32, v34
	v_add_f32_e64 v33, v33, v35
	ds_bpermute_b32 v35, v220, v33
	ds_bpermute_b32 v34, v220, v32
	s_waitcnt lgkmcnt(0)
	v_add_f32_e64 v32, v32, v34
	v_add_f32_e64 v33, v33, v35
	ds_bpermute_b32 v35, v214, v33
	ds_bpermute_b32 v34, v214, v32
	s_waitcnt lgkmcnt(0)
	v_add_f32_e64 v32, v32, v34
	v_add_f32_e64 v33, v33, v35
	v_mul_f32_e64 v32, v32, s10
	v_mul_f32_e64 v33, v33, s10
	v_mul_f32_e64 v34, v32, s12
	v_mul_f32_e64 v35, v33, s12
	v_mul_f32_e32 v36, 0.5, v33
	v_fma_f32 v33, |v35|, s36, 1.0
	v_div_scale_f32 v45, s[0:1], v33, v33, 1.0
	v_rcp_f32_e32 v48, v45
	v_div_scale_f32 v46, vcc, 1.0, v33, 1.0
	v_mul_f32_e64 v37, |v35|, -|v35|
	v_fma_f32 v51, -v45, v48, 1.0
	v_fmac_f32_e32 v48, v51, v48
	v_mul_f32_e32 v51, v46, v48
	v_fma_f32 v53, -v45, v51, v46
	v_fmac_f32_e32 v51, v53, v48
	v_fma_f32 v45, -v45, v51, v46
	v_div_fmas_f32 v45, v45, v48, v51
	v_div_fixup_f32 v33, v45, v33, 1.0
	v_fma_f32 v44, |v34|, s36, 1.0
	v_mul_f32_e32 v37, 0x3fb8aa3b, v37
	v_fmamk_f32 v45, v33, 0x3f87dc22, v223
	v_div_scale_f32 v47, s[0:1], v44, v44, 1.0
	v_exp_f32_e32 v37, v37
	v_fmaak_f32 v45, v33, v45, 0x3fb5f0e3
	v_rcp_f32_e32 v49, v47
	v_fmaak_f32 v45, v33, v45, 0xbe91a98e
	v_fmaak_f32 v45, v33, v45, 0x3e827906
	v_mul_f32_e32 v33, v33, v45
	v_fma_f32 v33, -v37, v33, 1.0
	v_cmp_gt_f32_e32 vcc, 0, v35
	v_fma_f32 v52, -v47, v49, 1.0
	v_div_scale_f32 v50, s[0:1], 1.0, v44, 1.0
	v_cndmask_b32_e64 v33, v33, -v33, vcc
	v_fmac_f32_e32 v49, v52, v49
	v_add_f32_e32 v33, 1.0, v33
	v_mul_f32_e32 v52, v50, v49
	v_mul_f32_e32 v33, v36, v33
	v_mul_f32_e32 v134, v134, v33
	v_fma_f32 v33, -v47, v52, v50
	v_fmac_f32_e32 v52, v33, v49
	v_fma_f32 v33, -v47, v52, v50
	s_mov_b64 vcc, s[0:1]
	v_div_fmas_f32 v33, v33, v49, v52
	v_div_fixup_f32 v33, v33, v44, 1.0
	v_mul_f32_e64 v36, |v34|, -|v34|
	v_fmamk_f32 v35, v33, 0x3f87dc22, v223
	v_mul_f32_e32 v36, 0x3fb8aa3b, v36
	v_fmaak_f32 v35, v33, v35, 0x3fb5f0e3
	v_exp_f32_e32 v36, v36
	v_fmaak_f32 v35, v33, v35, 0xbe91a98e
	v_fmaak_f32 v35, v33, v35, 0x3e827906
	v_mul_f32_e32 v33, v33, v35
	v_fma_f32 v33, -v36, v33, 1.0
	v_cmp_gt_f32_e32 vcc, 0, v34
	v_mul_f32_e32 v32, 0.5, v32
	s_nop 0
	v_cndmask_b32_e64 v33, v33, -v33, vcc
	v_add_f32_e32 v33, 1.0, v33
	v_mul_f32_e32 v32, v32, v33
	v_mul_f32_e32 v210, v135, v32
	s_waitcnt vmcnt(10)
	v_cvt_scalef32_pk32_f32_fp6 v[32:63], v[98:103], 1.0
	v_mov_b32_e32 v212, v209
	v_mov_b32_e32 v213, v97
	v_mov_b32_e32 v209, v96
	s_waitcnt vmcnt(8)
	v_cvt_scalef32_pk32_f32_fp6 v[96:127], v[128:133], 1.0
	v_fma_f32 v0, v0, v134, v206
	v_fma_f32 v1, v1, v134, v207
	v_add_f32_e64 v128, v212, v208
	v_add_f32_e64 v129, v213, v209
	v_fma_f32 v0, v64, v210, v0
	v_fma_f32 v1, v65, v210, v1
	ds_bpermute_b32 v65, v216, v129
	ds_bpermute_b32 v64, v216, v128
	v_fma_f32 v2, v2, v134, v204
	v_fma_f32 v3, v3, v134, v205
	v_fma_f32 v4, v4, v134, v202
	v_fma_f32 v5, v5, v134, v203
	v_fma_f32 v2, v66, v210, v2
	v_fma_f32 v3, v67, v210, v3
	v_fma_f32 v6, v6, v134, v200
	v_fma_f32 v7, v7, v134, v201
	s_waitcnt lgkmcnt(0)
	v_add_f32_e64 v64, v128, v64
	v_add_f32_e64 v65, v129, v65
	ds_bpermute_b32 v67, v217, v65
	ds_bpermute_b32 v66, v217, v64
	v_fma_f32 v8, v8, v134, v198
	v_fma_f32 v9, v9, v134, v199
	v_fma_f32 v4, v68, v210, v4
	v_fma_f32 v5, v69, v210, v5
	v_fma_f32 v10, v10, v134, v196
	v_fma_f32 v11, v11, v134, v197
	v_fma_f32 v12, v12, v134, v194
	v_fma_f32 v13, v13, v134, v195
	s_waitcnt lgkmcnt(0)
	v_add_f32_e64 v64, v64, v66
	v_add_f32_e64 v65, v65, v67
	ds_bpermute_b32 v67, v218, v65
	ds_bpermute_b32 v66, v218, v64
	v_fma_f32 v6, v70, v210, v6
	v_fma_f32 v7, v71, v210, v7
	v_fma_f32 v8, v72, v210, v8
	v_fma_f32 v9, v73, v210, v9
	v_fma_f32 v10, v74, v210, v10
	v_fma_f32 v11, v75, v210, v11
	v_fma_f32 v12, v76, v210, v12
	v_fma_f32 v13, v77, v210, v13
	s_waitcnt lgkmcnt(0)
; DI float my_erf(float x) {
;   const float ax = fabsf(x);
;   const float t = 1.f / (1.f + 0.3275911f * ax);
;   const float poly = t * (0.254829592f + t * (-0.284496736f + t * (1.421413741f + t * (-1.453152027f + t * 1.061405429f))));
;   const float r = 1.f - poly * __expf(-ax * ax);
;   return x < 0.f ? -r : r;
; __device__ __forceinline__ void phase_expert(const Params& p, int layer, int row0) {
;     ...
; #pragma unroll
;       for (int o = 32; o >= 1; o >>= 1) {
; #pragma unroll
;         for (int k = 0; k < 4; ++k) dk[k] += __shfl_xor(dk[k], o);
;       }
; #pragma unroll
;       for (int k = 0; k < 4; ++k) {
;         const float a = dk[k] * (1.f / SC_U);
;         const float w = gk[k] * (0.5f * a * (1.f + my_erf(a * 0.7071067811865476f)));
;         const u32x6 pk = {ua[k][0], ua[k][1], ua[k][2], ua[k][3], ub[k][0], ub[k][1]};
;         const f32x32 f = __builtin_amdgcn_cvt_scalef32_pk32_f32_fp6(pk, 1.0f);
; #pragma unroll
;         for (int j = 0; j < 32; ++j) y[j] += w * f[j];
;         __builtin_amdgcn_sched_barrier(0);
;       }
	v_add_f32_e64 v64, v64, v66
	v_add_f32_e64 v65, v65, v67
	ds_bpermute_b32 v67, v219, v65
	ds_bpermute_b32 v66, v219, v64
	v_fma_f32 v14, v14, v134, v192
	v_fma_f32 v15, v15, v134, v193
	v_fma_f32 v16, v16, v134, v190
	v_fma_f32 v17, v17, v134, v191
	v_fma_f32 v14, v78, v210, v14
	v_fma_f32 v15, v79, v210, v15
	v_fma_f32 v16, v80, v210, v16
	v_fma_f32 v17, v81, v210, v17
	s_waitcnt lgkmcnt(0)
	v_add_f32_e64 v64, v64, v66
	v_add_f32_e64 v65, v65, v67
	ds_bpermute_b32 v67, v220, v65
	ds_bpermute_b32 v66, v220, v64
	v_fma_f32 v18, v18, v134, v188
	v_fma_f32 v19, v19, v134, v189
	v_fma_f32 v20, v20, v134, v186
	v_fma_f32 v21, v21, v134, v187
	v_fma_f32 v22, v22, v134, v184
	v_fma_f32 v23, v23, v134, v185
	v_fma_f32 v24, v24, v134, v182
	v_fma_f32 v25, v25, v134, v183
	s_waitcnt lgkmcnt(0)
	v_add_f32_e64 v64, v64, v66
	v_add_f32_e64 v65, v65, v67
	ds_bpermute_b32 v67, v214, v65
	ds_bpermute_b32 v66, v214, v64
	v_fma_f32 v26, v26, v134, v180
	v_fma_f32 v27, v27, v134, v181
	v_fma_f32 v28, v28, v134, v178
	v_fma_f32 v29, v29, v134, v179
	v_fma_f32 v30, v30, v134, v162
	v_fma_f32 v31, v31, v134, v163
	v_fma_f32 v18, v82, v210, v18
	v_fma_f32 v19, v83, v210, v19
	s_waitcnt lgkmcnt(0)
	v_add_f32_e64 v64, v64, v66
	v_add_f32_e64 v65, v65, v67
	v_fma_f32 v20, v84, v210, v20
	v_fma_f32 v21, v85, v210, v21
	v_mul_f32_e64 v64, v64, s10
	v_mul_f32_e64 v65, v65, s10
	v_fma_f32 v22, v86, v210, v22
	v_fma_f32 v23, v87, v210, v23
	v_mul_f32_e64 v66, v64, s12
	v_mul_f32_e64 v67, v65, s12
	v_mul_f32_e32 v68, 0.5, v65
	v_mul_f32_e32 v65, 0.5, v64
	v_fma_f32 v64, |v67|, s36, 1.0
	v_fma_f32 v70, |v66|, s36, 1.0
	v_div_scale_f32 v72, s[0:1], v64, v64, 1.0
	v_div_scale_f32 v74, s[0:1], v70, v70, 1.0
	v_rcp_f32_e32 v76, v72
	v_rcp_f32_e32 v77, v74
	v_div_scale_f32 v73, vcc, 1.0, v64, 1.0
	v_fma_f32 v78, -v72, v76, 1.0
	v_fma_f32 v79, -v74, v77, 1.0
	v_fmac_f32_e32 v76, v78, v76
	v_div_scale_f32 v75, s[0:1], 1.0, v70, 1.0
	v_fmac_f32_e32 v77, v79, v77
	v_mul_f32_e32 v78, v73, v76
	v_mul_f32_e32 v79, v75, v77
	v_fma_f32 v80, -v72, v78, v73
	v_fma_f32 v81, -v74, v79, v75
	v_fmac_f32_e32 v78, v80, v76
	v_fmac_f32_e32 v79, v81, v77
	v_fma_f32 v72, -v72, v78, v73
	v_fma_f32 v73, -v74, v79, v75
	v_div_fmas_f32 v72, v72, v76, v78
	s_mov_b64 vcc, s[0:1]
	v_mul_f32_e64 v69, |v67|, -|v67|
	v_div_fixup_f32 v64, v72, v64, 1.0
	v_div_fmas_f32 v72, v73, v77, v79
	v_mul_f32_e64 v71, |v66|, -|v66|
	v_mul_f32_e32 v69, 0x3fb8aa3b, v69
	v_fmamk_f32 v73, v64, 0x3f87dc22, v223
	v_div_fixup_f32 v70, v72, v70, 1.0
	v_mul_f32_e32 v71, 0x3fb8aa3b, v71
	v_exp_f32_e32 v69, v69
	v_fmaak_f32 v72, v64, v73, 0x3fb5f0e3
	v_fmamk_f32 v73, v70, 0x3f87dc22, v223
	v_exp_f32_e32 v71, v71
	v_fmaak_f32 v72, v64, v72, 0xbe91a98e
	v_fmaak_f32 v73, v70, v73, 0x3fb5f0e3
	v_fmaak_f32 v72, v64, v72, 0x3e827906
	v_fmaak_f32 v73, v70, v73, 0xbe91a98e
	v_mul_f32_e32 v64, v64, v72
	v_fmaak_f32 v72, v70, v73, 0x3e827906
	v_fma_f32 v64, -v69, v64, 1.0
	v_cmp_gt_f32_e32 vcc, 0, v67
	v_mul_f32_e32 v67, v70, v72
	v_fma_f32 v67, -v71, v67, 1.0
	v_cmp_gt_f32_e64 s[0:1], 0, v66
	v_cndmask_b32_e64 v64, v64, -v64, vcc
	v_add_f32_e32 v64, 1.0, v64
	v_cndmask_b32_e64 v66, v67, -v67, s[0:1]
	v_mul_f32_e32 v64, v68, v64
	v_add_f32_e32 v66, 1.0, v66
	v_fma_f32 v24, v88, v210, v24
	v_fma_f32 v25, v89, v210, v25
	v_fma_f32 v26, v90, v210, v26
	v_fma_f32 v27, v91, v210, v27
	v_fma_f32 v28, v92, v210, v28
	v_fma_f32 v29, v93, v210, v29
	v_fma_f32 v30, v94, v210, v30
	v_fma_f32 v31, v95, v210, v31
	v_mul_f32_e32 v64, v136, v64
	v_mul_f32_e32 v65, v65, v66
	v_mul_f32_e32 v66, v137, v65
	v_fma_f32 v0, v32, v64, v0
	v_fma_f32 v1, v33, v64, v1
	v_fma_f32 v2, v34, v64, v2
	v_fma_f32 v3, v35, v64, v3
	v_fma_f32 v4, v36, v64, v4
	v_fma_f32 v5, v37, v64, v5
	v_fma_f32 v6, v38, v64, v6
	v_fma_f32 v7, v39, v64, v7
	v_fma_f32 v8, v40, v64, v8
	v_fma_f32 v9, v41, v64, v9
	v_fma_f32 v10, v42, v64, v10
	v_fma_f32 v11, v43, v64, v11
	v_fma_f32 v12, v44, v64, v12
	v_fma_f32 v13, v45, v64, v13
	v_fma_f32 v14, v46, v64, v14
	v_fma_f32 v15, v47, v64, v15
	v_fma_f32 v16, v48, v64, v16
	v_fma_f32 v17, v49, v64, v17
	v_fma_f32 v18, v50, v64, v18
	v_fma_f32 v19, v51, v64, v19
	v_fma_f32 v20, v52, v64, v20
	v_fma_f32 v21, v53, v64, v21
	v_fma_f32 v22, v54, v64, v22
	v_fma_f32 v23, v55, v64, v23
	v_fma_f32 v24, v56, v64, v24
	v_fma_f32 v25, v57, v64, v25
	v_fma_f32 v26, v58, v64, v26
	v_fma_f32 v27, v59, v64, v27
	v_fma_f32 v28, v60, v64, v28
	v_fma_f32 v29, v61, v64, v29
	v_fma_f32 v30, v62, v64, v30
	v_fma_f32 v31, v63, v64, v31
	v_fma_f32 v206, v96, v66, v0
	v_fma_f32 v207, v97, v66, v1
	v_fma_f32 v204, v98, v66, v2
	v_fma_f32 v205, v99, v66, v3
	v_fma_f32 v202, v100, v66, v4
	v_fma_f32 v203, v101, v66, v5
	v_fma_f32 v200, v102, v66, v6
	v_fma_f32 v201, v103, v66, v7
	v_fma_f32 v198, v104, v66, v8
	v_fma_f32 v199, v105, v66, v9
	v_fma_f32 v196, v106, v66, v10
	v_fma_f32 v197, v107, v66, v11
	v_fma_f32 v194, v108, v66, v12
	v_fma_f32 v195, v109, v66, v13
	v_fma_f32 v192, v110, v66, v14
	v_fma_f32 v193, v111, v66, v15
	v_fma_f32 v190, v112, v66, v16
	v_fma_f32 v191, v113, v66, v17
	v_fma_f32 v188, v114, v66, v18
	v_fma_f32 v189, v115, v66, v19
	v_fma_f32 v186, v116, v66, v20
	v_fma_f32 v187, v117, v66, v21
	v_fma_f32 v184, v118, v66, v22
	v_fma_f32 v185, v119, v66, v23
	v_fma_f32 v182, v120, v66, v24
	v_fma_f32 v183, v121, v66, v25
	v_fma_f32 v180, v122, v66, v26
	v_fma_f32 v181, v123, v66, v27
	v_fma_f32 v178, v124, v66, v28
	v_fma_f32 v179, v125, v66, v29
	v_fma_f32 v162, v126, v66, v30
	v_fma_f32 v163, v127, v66, v31
	s_add_i32 s42, s42, 4
	s_add_u32 s28, s28, 16
	s_addc_u32 s29, s29, 0
	s_cmpk_gt_u32 s42, 0x7b
	s_cbranch_scc0 .LBB0_2561
; DI const float* modp(const Params& p, int layer, int v) { return (const float*)(p.ws + OFF_MOD) + (size_t)(layer * 2 + v) * 12288; }
; __device__ __forceinline__ void phase_expert(const Params& p, int layer, int row0) {
;     ...
;     int lane2 = lane; asm volatile("" : "+v"(lane2));
;     const int v = row < NCTX ? 1 : 0;
;     const float* md = modp(p, layer, v);
;     float pre[32];
;     float s = 0.f;
; #pragma unroll
;     for (int c = 0; c < 2; ++c) {
; #pragma unroll
;       for (int q4 = 0; q4 < 4; ++q4) {
;         const int col = c * 1024 + lane2 * 16 + q4 * 4;
;         const f32x4 a = *(const f32x4*)(XR + (size_t)row * LDF + col);
;         const f32x4 g2 = *(const f32x4*)(md + 10240 + col);
; #pragma unroll
;         for (int e = 0; e < 4; ++e) {
;           const float pv = ALPHA * a[e] + g2[e] * (y[c * 16 + q4 * 4 + e] * (1.f / SC_V));
;           pre[c * 16 + q4 * 4 + e] = pv; s += pv;
;         }
;       }
;     }
;     const float mu = wave_sum(s) * (1.f / 2048.f);
	v_mov_b32_e32 v0, v211
	s_cmpk_lt_i32 s26, 0x100
	s_cselect_b32 s0, s37, 0x18000
	v_lshlrev_b32_e32 v0, 4, v0
	s_add_u32 s0, s4, s0
	v_ashrrev_i32_e32 v1, 31, v0
	s_addc_u32 s1, s5, 0
	v_lshlrev_b64 v[2:3], 2, v[0:1]
	v_lshl_add_u64 v[16:17], s[0:1], 0, v[2:3]
	s_mul_i32 s0, s26, 0x2080
	v_add_co_u32_e32 v30, vcc, s39, v16
	s_mul_hi_i32 s1, s26, 0x2080
	s_add_u32 s0, s33, s0
	v_lshl_add_u64 v[28:29], v[16:17], 0, s[14:15]
	v_lshl_add_u64 v[56:57], v[16:17], 0, s[20:21]
	v_addc_co_u32_e32 v31, vcc, 0, v17, vcc
	s_addc_u32 s1, s34, s1
	global_load_dwordx4 v[4:7], v[28:29], off offset:32
	global_load_dwordx4 v[8:11], v[28:29], off offset:16
	global_load_dwordx4 v[12:15], v[56:57], off offset:48
	global_load_dwordx4 v[16:19], v[30:31], off offset:-4096
	global_load_dwordx4 v[20:23], v[56:57], off offset:32
	global_load_dwordx4 v[24:27], v[28:29], off offset:48
	v_lshl_add_u64 v[58:59], s[0:1], 0, v[2:3]
	v_lshl_add_u64 v[68:69], v[58:59], 0, s[18:19]
	global_load_dwordx4 v[28:31], v[30:31], off
	s_nop 0
	global_load_dwordx4 v[32:35], v[68:69], off offset:48
	global_load_dwordx4 v[36:39], v[58:59], off offset:16
	global_load_dwordx4 v[40:43], v[58:59], off
	global_load_dwordx4 v[44:47], v[58:59], off offset:32
	global_load_dwordx4 v[48:51], v[58:59], off offset:48
	global_load_dwordx4 v[52:55], v[56:57], off offset:16
	v_add_co_u32_e32 v70, vcc, s38, v58
	v_mul_f32_e64 v72, v202, s16
	v_mul_f32_e64 v73, v203, s16
	s_nop 0
	v_addc_co_u32_e32 v71, vcc, 0, v59, vcc
	global_load_dwordx4 v[56:59], v[70:71], off
	global_load_dwordx4 v[60:63], v[68:69], off offset:32
	global_load_dwordx4 v[64:67], v[68:69], off offset:16
	v_mul_f32_e64 v68, v206, s16
	v_mul_f32_e64 v69, v207, s16
	v_mul_f32_e64 v70, v204, s16
	v_mul_f32_e64 v71, v205, s16
	v_mul_f32_e64 v74, v200, s16
	v_mul_f32_e64 v75, v201, s16
	v_mul_f32_e64 v76, v198, s16
	v_mul_f32_e64 v77, v199, s16
	v_mul_f32_e64 v78, v196, s16
	v_mul_f32_e64 v79, v197, s16
	v_mul_f32_e64 v80, v194, s16
	v_mul_f32_e64 v81, v195, s16
	v_mul_f32_e64 v82, v192, s16
	v_mul_f32_e64 v83, v193, s16
	v_mul_f32_e64 v84, v190, s16
	v_mul_f32_e64 v85, v191, s16
	v_mul_f32_e64 v86, v188, s16
	v_mul_f32_e64 v87, v189, s16
	v_mul_f32_e64 v88, v186, s16
	v_mul_f32_e64 v89, v187, s16
	v_mul_f32_e64 v90, v184, s16
	v_mul_f32_e64 v91, v185, s16
	v_mul_f32_e64 v92, v182, s16
	v_mul_f32_e64 v93, v183, s16
	v_mul_f32_e64 v94, v180, s16
	v_mul_f32_e64 v95, v181, s16
	v_mul_f32_e64 v96, v178, s16
	v_mul_f32_e64 v97, v179, s16
	v_mul_f32_e64 v98, v162, s16
	v_mul_f32_e64 v99, v163, s16
	s_add_i32 s0, s26, 0xffffff00
	s_ashr_i32 s1, s0, 31
	s_lshl_b64 s[0:1], s[0:1], 13
	s_add_u32 s0, s84, s0
	s_addc_u32 s1, s85, s1
	v_add_u32_e32 v215, s35, v215
	s_waitcnt vmcnt(15)
	v_mul_f32_e64 v4, v76, v4
	v_mul_f32_e64 v5, v77, v5
	s_waitcnt vmcnt(12)
	v_mul_f32_e64 v16, v68, v16
	v_mul_f32_e64 v17, v69, v17
	v_mul_f32_e64 v18, v70, v18
	v_mul_f32_e64 v19, v71, v19
	v_mul_f32_e64 v8, v72, v8
	v_mul_f32_e64 v9, v73, v9
	s_waitcnt vmcnt(6)
	v_fma_f32 v40, v40, s22, v16
	v_fma_f32 v41, v41, s22, v17
	v_fma_f32 v42, v42, s22, v18
	v_fma_f32 v43, v43, s22, v19
	v_add_f32_e32 v1, 0, v40
	v_add_f32_e32 v1, v41, v1
	v_add_f32_e32 v1, v42, v1
	v_fma_f32 v36, v36, s22, v8
	v_fma_f32 v37, v37, s22, v9
	v_add_f32_e32 v1, v43, v1
	v_mul_f32_e64 v10, v74, v10
	v_mul_f32_e64 v11, v75, v11
	v_add_f32_e32 v1, v36, v1
	v_fma_f32 v38, v38, s22, v10
	v_fma_f32 v39, v39, s22, v11
	v_add_f32_e32 v1, v37, v1
	v_add_f32_e32 v1, v38, v1
	s_waitcnt vmcnt(5)
	v_fma_f32 v44, v44, s22, v4
	v_fma_f32 v45, v45, s22, v5
	v_add_f32_e32 v1, v39, v1
	v_mul_f32_e64 v6, v78, v6
	v_mul_f32_e64 v7, v79, v7
	v_add_f32_e32 v1, v44, v1
	v_fma_f32 v46, v46, s22, v6
	v_fma_f32 v47, v47, s22, v7
	v_add_f32_e32 v1, v45, v1
	v_mul_f32_e64 v24, v80, v24
	v_mul_f32_e64 v25, v81, v25
	v_add_f32_e32 v1, v46, v1
	s_waitcnt vmcnt(4)
	v_fma_f32 v24, v48, s22, v24
	v_fma_f32 v25, v49, s22, v25
	v_add_f32_e32 v1, v47, v1
	v_mul_f32_e64 v26, v82, v26
	v_mul_f32_e64 v27, v83, v27
	v_add_f32_e32 v1, v24, v1
	v_fma_f32 v26, v50, s22, v26
	v_fma_f32 v27, v51, s22, v27
	v_add_f32_e32 v1, v25, v1
	v_mul_f32_e64 v28, v84, v28
	v_mul_f32_e64 v29, v85, v29
	v_add_f32_e32 v1, v26, v1
	s_waitcnt vmcnt(2)
	v_fma_f32 v28, v56, s22, v28
	v_fma_f32 v29, v57, s22, v29
	v_add_f32_e32 v1, v27, v1
	v_mul_f32_e64 v30, v86, v30
	v_mul_f32_e64 v31, v87, v31
	v_add_f32_e32 v1, v28, v1
	v_fma_f32 v30, v58, s22, v30
	v_fma_f32 v31, v59, s22, v31
	v_add_f32_e32 v1, v29, v1
	v_mul_f32_e64 v4, v88, v52
	v_mul_f32_e64 v5, v89, v53
	v_add_f32_e32 v1, v30, v1
	s_waitcnt vmcnt(0)
	v_fma_f32 v48, v64, s22, v4
	v_fma_f32 v49, v65, s22, v5
	v_add_f32_e32 v1, v31, v1
	v_mul_f32_e64 v6, v90, v54
	v_mul_f32_e64 v7, v91, v55
	v_add_f32_e32 v1, v48, v1
	v_fma_f32 v50, v66, s22, v6
	v_fma_f32 v51, v67, s22, v7
	v_add_f32_e32 v1, v49, v1
	v_mul_f32_e64 v20, v92, v20
	v_mul_f32_e64 v21, v93, v21
	v_add_f32_e32 v1, v50, v1
	v_fma_f32 v20, v60, s22, v20
	v_fma_f32 v21, v61, s22, v21
	v_add_f32_e32 v1, v51, v1
	v_mul_f32_e64 v22, v94, v22
	v_mul_f32_e64 v23, v95, v23
	v_add_f32_e32 v1, v20, v1
	v_add_f32_e32 v1, v21, v1
	v_fma_f32 v22, v62, s22, v22
	v_fma_f32 v23, v63, s22, v23
	v_mul_f32_e64 v12, v96, v12
	v_mul_f32_e64 v13, v97, v13
	v_add_f32_e32 v1, v22, v1
	v_fma_f32 v32, v32, s22, v12
	v_fma_f32 v33, v33, s22, v13
	v_add_f32_e32 v1, v23, v1
	v_mul_f32_e64 v14, v98, v14
	v_mul_f32_e64 v15, v99, v15
	v_add_f32_e32 v1, v32, v1
	v_fma_f32 v34, v34, s22, v14
	v_fma_f32 v35, v35, s22, v15
	v_add_f32_e32 v1, v33, v1
	v_add_f32_e32 v1, v34, v1
	v_add_f32_e32 v1, v35, v1
	ds_bpermute_b32 v4, v216, v1
	v_lshl_add_u64 v[52:53], s[6:7], 0, v[2:3]
	v_lshl_add_u64 v[54:55], s[8:9], 0, v[2:3]
	s_waitcnt lgkmcnt(0)
; DI const float* modp(const Params& p, int layer, int v) { return (const float*)(p.ws + OFF_MOD) + (size_t)(layer * 2 + v) * 12288; }
; __device__ __forceinline__ void phase_expert(const Params& p, int layer, int row0) {
;     ...
;     const float mu = wave_sum(s) * (1.f / 2048.f);
;     float q = 0.f;
; #pragma unroll
;     for (int e = 0; e < 32; ++e) { float d = pre[e] - mu; q += d * d; }
;     const float rstd = rsqrtf(wave_sum(q) * (1.f / 2048.f) + LN_EPS);
;     const float* mdn = modp(p, 1, v);
; #pragma unroll
;     for (int c = 0; c < 2; ++c) {
; #pragma unroll
;       for (int q8 = 0; q8 < 2; ++q8) {
;         const int col = c * 1024 + lane2 * 16 + q8 * 8;
;         float o[8];
; #pragma unroll
;         for (int e = 0; e < 8; ++e) o[e] = (pre[c * 16 + q8 * 8 + e] - mu) * rstd * G[col + e] + B[col + e];
	v_add_f32_e32 v1, v1, v4
	ds_bpermute_b32 v4, v217, v1
	s_waitcnt lgkmcnt(0)
	v_add_f32_e32 v1, v1, v4
	ds_bpermute_b32 v4, v218, v1
	s_waitcnt lgkmcnt(0)
	v_add_f32_e32 v1, v1, v4
	ds_bpermute_b32 v4, v219, v1
	s_waitcnt lgkmcnt(0)
	v_add_f32_e32 v1, v1, v4
	ds_bpermute_b32 v4, v220, v1
	s_waitcnt lgkmcnt(0)
	v_add_f32_e32 v1, v1, v4
	ds_bpermute_b32 v56, v214, v1
	global_load_dwordx4 v[4:7], v[52:53], off offset:16
	global_load_dwordx4 v[8:11], v[52:53], off
	global_load_dwordx4 v[12:15], v[54:55], off offset:16
	global_load_dwordx4 v[16:19], v[54:55], off
	s_waitcnt lgkmcnt(0)
	v_add_f32_e32 v1, v1, v56
	v_mul_f32_e32 v56, 0x3a000000, v1
	v_add_f32_e64 v40, v40, -v56
	v_add_f32_e64 v41, v41, -v56
	v_add_f32_e64 v42, v42, -v56
	v_add_f32_e64 v43, v43, -v56
	v_mul_f32_e64 v58, v40, v40
	v_mul_f32_e64 v59, v41, v41
	v_mul_f32_e64 v60, v42, v42
	v_mul_f32_e64 v61, v43, v43
	v_add_f32_e32 v1, v58, v59
	v_add_f32_e64 v36, v36, -v56
	v_add_f32_e64 v37, v37, -v56
	v_add_f32_e32 v1, v60, v1
	v_mul_f32_e64 v62, v36, v36
	v_mul_f32_e64 v63, v37, v37
	v_add_f32_e32 v1, v61, v1
	v_add_f32_e64 v38, v38, -v56
	v_add_f32_e64 v39, v39, -v56
	v_add_f32_e32 v1, v62, v1
	v_mul_f32_e64 v64, v38, v38
	v_mul_f32_e64 v65, v39, v39
	v_add_f32_e32 v1, v63, v1
	v_add_f32_e64 v44, v44, -v56
	v_add_f32_e64 v45, v45, -v56
	v_add_f32_e32 v1, v64, v1
	v_mul_f32_e64 v66, v44, v44
	v_mul_f32_e64 v67, v45, v45
	v_add_f32_e32 v1, v65, v1
	v_add_f32_e64 v46, v46, -v56
	v_add_f32_e64 v47, v47, -v56
	v_add_f32_e32 v1, v66, v1
	v_mul_f32_e64 v68, v46, v46
	v_mul_f32_e64 v69, v47, v47
	v_add_f32_e32 v1, v67, v1
	v_add_f32_e64 v24, v24, -v56
	v_add_f32_e64 v25, v25, -v56
	v_add_f32_e32 v1, v68, v1
	v_mul_f32_e64 v70, v24, v24
	v_mul_f32_e64 v71, v25, v25
	v_add_f32_e32 v1, v69, v1
	v_add_f32_e64 v26, v26, -v56
	v_add_f32_e64 v27, v27, -v56
	v_add_f32_e32 v1, v70, v1
	v_mul_f32_e64 v72, v26, v26
	v_mul_f32_e64 v73, v27, v27
	v_add_f32_e32 v1, v71, v1
	v_add_f32_e64 v28, v28, -v56
	v_add_f32_e64 v29, v29, -v56
	v_add_f32_e32 v1, v72, v1
	v_mul_f32_e64 v74, v28, v28
	v_mul_f32_e64 v75, v29, v29
	v_add_f32_e32 v1, v73, v1
	v_add_f32_e64 v30, v30, -v56
	v_add_f32_e64 v31, v31, -v56
	v_add_f32_e32 v1, v74, v1
	v_mul_f32_e64 v76, v30, v30
	v_mul_f32_e64 v77, v31, v31
	v_add_f32_e32 v1, v75, v1
	v_add_f32_e64 v48, v48, -v56
	v_add_f32_e64 v49, v49, -v56
	v_add_f32_e32 v1, v76, v1
	v_mul_f32_e64 v78, v48, v48
	v_mul_f32_e64 v79, v49, v49
	v_add_f32_e32 v1, v77, v1
	v_add_f32_e64 v50, v50, -v56
	v_add_f32_e64 v51, v51, -v56
	v_add_f32_e32 v1, v78, v1
	v_mul_f32_e64 v80, v50, v50
	v_mul_f32_e64 v81, v51, v51
	v_add_f32_e32 v1, v79, v1
	v_add_f32_e64 v20, v20, -v56
	v_add_f32_e64 v21, v21, -v56
	v_add_f32_e32 v1, v80, v1
	v_mul_f32_e64 v82, v20, v20
	v_mul_f32_e64 v83, v21, v21
	v_add_f32_e32 v1, v81, v1
	v_add_f32_e64 v22, v22, -v56
	v_add_f32_e64 v23, v23, -v56
	v_add_f32_e32 v1, v82, v1
	v_mul_f32_e64 v84, v22, v22
	v_mul_f32_e64 v85, v23, v23
	v_add_f32_e32 v1, v83, v1
	v_add_f32_e64 v32, v32, -v56
	v_add_f32_e64 v33, v33, -v56
	v_add_f32_e32 v1, v84, v1
	v_mul_f32_e64 v86, v32, v32
	v_mul_f32_e64 v87, v33, v33
	v_add_f32_e32 v1, v85, v1
	v_add_f32_e64 v34, v34, -v56
	v_add_f32_e64 v35, v35, -v56
	v_add_f32_e32 v1, v86, v1
	v_mul_f32_e64 v56, v34, v34
	v_mul_f32_e64 v57, v35, v35
	v_add_f32_e32 v1, v87, v1
	v_add_f32_e32 v1, v56, v1
	v_add_f32_e32 v1, v57, v1
	ds_bpermute_b32 v56, v216, v1
	s_waitcnt lgkmcnt(0)
	v_add_f32_e32 v1, v1, v56
	ds_bpermute_b32 v56, v217, v1
	s_waitcnt lgkmcnt(0)
	v_add_f32_e32 v1, v1, v56
	ds_bpermute_b32 v56, v218, v1
	s_waitcnt lgkmcnt(0)
	v_add_f32_e32 v1, v1, v56
	ds_bpermute_b32 v56, v219, v1
	s_waitcnt lgkmcnt(0)
	v_add_f32_e32 v1, v1, v56
	ds_bpermute_b32 v58, v220, v1
	v_or_b32_e32 v56, 8, v0
	v_ashrrev_i32_e32 v57, 31, v56
	v_lshlrev_b64 v[56:57], 2, v[56:57]
	s_waitcnt lgkmcnt(0)
	v_add_f32_e32 v1, v1, v58
	ds_bpermute_b32 v60, v214, v1
	v_lshl_add_u64 v[58:59], s[6:7], 0, v[56:57]
	v_lshl_add_u64 v[56:57], s[8:9], 0, v[56:57]
	s_waitcnt lgkmcnt(0)
; DI unsigned pk2(float a, float b) { f32x2 v = {a, b}; bf2_t r = __builtin_convertvector(v, bf2_t); return __builtin_bit_cast(unsigned, r); }
; DI const float* modp(const Params& p, int layer, int v) { return (const float*)(p.ws + OFF_MOD) + (size_t)(layer * 2 + v) * 12288; }
; __device__ __forceinline__ void phase_expert(const Params& p, int layer, int row0) {
;     ...
;     const float rstd = rsqrtf(wave_sum(q) * (1.f / 2048.f) + LN_EPS);
;     const float* mdn = modp(p, 1, v);
; #pragma unroll
;     for (int c = 0; c < 2; ++c) {
; #pragma unroll
;       for (int q8 = 0; q8 < 2; ++q8) {
;         const int col = c * 1024 + lane2 * 16 + q8 * 8;
;         float o[8];
; #pragma unroll
;         for (int e = 0; e < 8; ++e) o[e] = (pre[c * 16 + q8 * 8 + e] - mu) * rstd * G[col + e] + B[col + e];
;         if (layer == 0) {
;           *(f32x4*)(XR + (size_t)row * LDF + col) = f32x4{o[0], o[1], o[2], o[3]};
;           *(f32x4*)(XR + (size_t)row * LDF + col + 4) = f32x4{o[4], o[5], o[6], o[7]};
;           float z[8];
; #pragma unroll
;           for (int e = 0; e < 8; ++e) z[e] = o[e] * (1.f + mdn[2048 + col + e]) + mdn[col + e];
;           *(u32x4*)(XMo + (size_t)row * LDX + col) = u32x4{pk2(z[0], z[1]), pk2(z[2], z[3]), pk2(z[4], z[5]), pk2(z[6], z[7])};
;         } else {
;           float* out = p.out + (size_t)(row - NCTX) * DM + col;
;           *(f32x4*)(out) = f32x4{o[0], o[1], o[2], o[3]};
;           *(f32x4*)(out + 4) = f32x4{o[4], o[5], o[6], o[7]};
;         }
;       }
;     }
;   }
	v_add_f32_e32 v1, v1, v60
	v_fmamk_f32 v1, v1, 0x3a000000, v224
	v_mul_f32_e32 v60, 0x4b800000, v1
	v_cmp_gt_f32_e32 vcc, s40, v1
	s_nop 1
	v_cndmask_b32_e32 v1, v1, v60, vcc
	v_rsq_f32_e32 v1, v1
	v_lshl_add_u64 v[60:61], s[0:1], 0, v[2:3]
	v_mul_f32_e32 v2, 0x45800000, v1
	v_cndmask_b32_e32 v62, v1, v2, vcc
	v_mul_f32_e64 v2, v40, v62
	v_mul_f32_e64 v3, v41, v62
	v_mul_f32_e64 v40, v42, v62
	v_mul_f32_e64 v41, v43, v62
	s_waitcnt vmcnt(0)
	v_fma_f32 v8, v8, v2, v16
	v_fma_f32 v9, v9, v3, v17
	v_fma_f32 v10, v10, v40, v18
	v_fma_f32 v11, v11, v41, v19
	v_mul_f32_e64 v2, v36, v62
	v_mul_f32_e64 v3, v37, v62
	v_mul_f32_e64 v16, v38, v62
	v_mul_f32_e64 v17, v39, v62
	v_fma_f32 v4, v4, v2, v12
	v_fma_f32 v5, v5, v3, v13
	v_fma_f32 v6, v6, v16, v14
	v_fma_f32 v7, v7, v17, v15
	global_store_dwordx4 v[60:61], v[8:11], off
	global_store_dwordx4 v[60:61], v[4:7], off offset:16
	global_load_dwordx4 v[2:5], v[56:57], off
	s_nop 0
	global_load_dwordx4 v[6:9], v[58:59], off
	global_load_dwordx4 v[10:13], v[58:59], off offset:16
	global_load_dwordx4 v[14:17], v[56:57], off offset:16
	v_add_u32_e32 v18, 0x402, v0
	v_add_co_u32_e32 v38, vcc, s38, v52
	v_mul_f32_e64 v42, v46, v62
	v_mul_f32_e64 v43, v47, v62
	v_mul_f32_e64 v44, v44, v62
	v_mul_f32_e64 v45, v45, v62
	v_ashrrev_i32_e32 v19, 31, v18
	v_addc_co_u32_e32 v39, vcc, 0, v53, vcc
	v_mul_f32_e64 v26, v26, v62
	v_mul_f32_e64 v27, v27, v62
	v_mul_f32_e64 v24, v24, v62
	v_mul_f32_e64 v25, v25, v62
	v_lshlrev_b64 v[18:19], 2, v[18:19]
	v_add_co_u32_e32 v40, vcc, s38, v54
	v_lshl_add_u64 v[36:37], s[6:7], 0, v[18:19]
	v_lshl_add_u64 v[18:19], s[8:9], 0, v[18:19]
	v_addc_co_u32_e32 v41, vcc, 0, v55, vcc
	v_add_u32_e32 v0, 0x40a, v0
	v_ashrrev_i32_e32 v1, 31, v0
	v_lshlrev_b64 v[0:1], 2, v[0:1]
	v_mul_f32_e64 v30, v30, v62
	v_mul_f32_e64 v31, v31, v62
	v_mul_f32_e64 v20, v20, v62
	v_mul_f32_e64 v21, v21, v62
	s_waitcnt vmcnt(2)
	v_fma_f32 v2, v6, v44, v2
	v_fma_f32 v3, v7, v45, v3
	v_fma_f32 v4, v8, v42, v4
	v_fma_f32 v5, v9, v43, v5
	s_waitcnt vmcnt(0)
	v_fma_f32 v6, v10, v24, v14
	v_fma_f32 v7, v11, v25, v15
	v_fma_f32 v8, v12, v26, v16
	v_fma_f32 v9, v13, v27, v17
	global_store_dwordx4 v[60:61], v[2:5], off offset:32
	global_store_dwordx4 v[60:61], v[6:9], off offset:48
	global_load_dwordx2 v[10:11], v[38:39], off
	global_load_dwordx2 v[12:13], v[40:41], off
	global_load_dwordx2 v[14:15], v[36:37], off offset:16
	s_nop 0
	global_load_dwordx4 v[2:5], v[36:37], off
	global_load_dwordx4 v[6:9], v[18:19], off
	global_load_dwordx2 v[16:17], v[18:19], off offset:16
	v_lshl_add_u64 v[18:19], s[6:7], 0, v[0:1]
	v_lshl_add_u64 v[24:25], s[8:9], 0, v[0:1]
	v_add_co_u32_e32 v36, vcc, s38, v60
	v_mul_f32_e64 v0, v28, v62
	v_mul_f32_e64 v1, v29, v62
	s_nop 0
	v_addc_co_u32_e32 v37, vcc, 0, v61, vcc
	v_mul_f32_e64 v28, v48, v62
	v_mul_f32_e64 v29, v49, v62
	v_mul_f32_e64 v42, v50, v62
	v_mul_f32_e64 v43, v51, v62
	v_lshl_add_u64 v[26:27], v[60:61], 0, s[18:19]
	v_cmp_lt_i32_e32 vcc, s41, v215
	s_or_b64 s[2:3], vcc, s[2:3]
	s_waitcnt vmcnt(4)
	v_fma_f32 v0, v10, v0, v12
	v_fma_f32 v1, v11, v1, v13
	s_waitcnt vmcnt(1)
	v_fma_f32 v2, v2, v30, v6
	v_fma_f32 v3, v3, v31, v7
	s_waitcnt vmcnt(0)
	v_fma_f32 v6, v14, v42, v16
	v_fma_f32 v7, v15, v43, v17
	v_fma_f32 v4, v4, v28, v8
	v_fma_f32 v5, v5, v29, v9
	global_store_dwordx4 v[36:37], v[0:3], off
	global_store_dwordx4 v[26:27], v[4:7], off offset:16
	global_load_dwordx2 v[8:9], v[38:39], off offset:32
	global_load_dwordx2 v[10:11], v[40:41], off offset:32
	global_load_dwordx2 v[12:13], v[18:19], off offset:16
	s_nop 0
	global_load_dwordx4 v[0:3], v[18:19], off
	global_load_dwordx4 v[4:7], v[24:25], off
	global_load_dwordx2 v[14:15], v[24:25], off offset:16
	v_mul_f32_e64 v18, v22, v62
	v_mul_f32_e64 v19, v23, v62
	v_mul_f32_e64 v22, v32, v62
	v_mul_f32_e64 v23, v33, v62
	v_mul_f32_e64 v24, v34, v62
	v_mul_f32_e64 v25, v35, v62
	v_lshl_add_u64 v[16:17], v[60:61], 0, s[24:25]
	s_waitcnt vmcnt(4)
	v_fma_f32 v8, v8, v20, v10
	v_fma_f32 v9, v9, v21, v11
	s_waitcnt vmcnt(1)
	v_fma_f32 v10, v0, v18, v4
	v_fma_f32 v11, v1, v19, v5
	s_waitcnt vmcnt(0)
	v_fma_f32 v4, v24, v12, v14
	v_fma_f32 v5, v25, v13, v15
	v_fma_f32 v2, v22, v2, v6
	v_fma_f32 v3, v23, v3, v7
	global_store_dwordx4 v[36:37], v[8:11], off offset:32
	global_store_dwordx4 v[16:17], v[2:5], off offset:16
	s_andn2_b64 exec, exec, s[2:3]
	s_cbranch_execnz .LBB0_2560
